# MLA+DSA attention: 3-slot LDS ring with K/V prefetched two tiles ahead (counted vmcnt); indexer select loop: SGPR-pair compares without vcc nops, DPP butterfly reduction
# speedup vs baseline: 1.0191x; 1.0072x over previous
; DI void indexer_phase(const u16* __restrict__ P, unsigned* __restrict__ mask) {
;     ...
;     const int target = (tme + 1 < 256) ? tme + 1 : 256;
;     unsigned T = 0u;
;     ...
;       const unsigned Tp = T | (1u << bit);
;       int cnt = 0;
; #pragma unroll
;       for (int kb = 0; kb < 64; ++kb) cnt += (sc[kb] >= Tp) ? 1 : 0;
; #pragma unroll
;       for (int o = 16; o; o >>= 1) cnt += __shfl_xor(cnt, o);
;       if (cnt >= target) T = Tp;
;     }
.LBB0_974:
	s_lshl_b32 s1, 1, s0
	v_or_b32_e32 v9, s1, v144
	s_add_i32 s0, s0, -1
	s_cmp_eq_u32 s0, -1
	v_mov_b32_e32 v10, 0
	v_mov_b32_e32 v11, 0
	v_cmp_ge_u32_e64 s[36:37], v146, v9
	v_cmp_ge_u32_e64 s[38:39], v2, v9
	v_cmp_ge_u32_e64 s[40:41], v145, v9
	v_cmp_ge_u32_e64 s[42:43], v148, v9
	v_cmp_ge_u32_e64 s[44:45], v147, v9
	v_cmp_ge_u32_e64 s[46:47], v150, v9
	v_cmp_ge_u32_e64 s[48:49], v149, v9
	v_cmp_ge_u32_e64 s[50:51], v152, v9
	v_addc_co_u32_e64 v10, s[66:67], 0, v10, s[36:37]
	v_addc_co_u32_e64 v11, s[68:69], 0, v11, s[38:39]
	v_addc_co_u32_e64 v10, s[66:67], 0, v10, s[40:41]
	v_addc_co_u32_e64 v11, s[68:69], 0, v11, s[42:43]
	v_addc_co_u32_e64 v10, s[66:67], 0, v10, s[44:45]
	v_addc_co_u32_e64 v11, s[68:69], 0, v11, s[46:47]
	v_addc_co_u32_e64 v10, s[66:67], 0, v10, s[48:49]
	v_addc_co_u32_e64 v11, s[68:69], 0, v11, s[50:51]
	v_cmp_ge_u32_e64 s[36:37], v151, v9
	v_cmp_ge_u32_e64 s[38:39], v154, v9
	v_cmp_ge_u32_e64 s[40:41], v153, v9
	v_cmp_ge_u32_e64 s[42:43], v156, v9
	v_cmp_ge_u32_e64 s[44:45], v155, v9
	v_cmp_ge_u32_e64 s[46:47], v158, v9
	v_cmp_ge_u32_e64 s[48:49], v157, v9
	v_cmp_ge_u32_e64 s[50:51], v160, v9
	v_addc_co_u32_e64 v10, s[66:67], 0, v10, s[36:37]
	v_addc_co_u32_e64 v11, s[68:69], 0, v11, s[38:39]
	v_addc_co_u32_e64 v10, s[66:67], 0, v10, s[40:41]
	v_addc_co_u32_e64 v11, s[68:69], 0, v11, s[42:43]
	v_addc_co_u32_e64 v10, s[66:67], 0, v10, s[44:45]
	v_addc_co_u32_e64 v11, s[68:69], 0, v11, s[46:47]
	v_addc_co_u32_e64 v10, s[66:67], 0, v10, s[48:49]
	v_addc_co_u32_e64 v11, s[68:69], 0, v11, s[50:51]
	v_cmp_ge_u32_e64 s[36:37], v159, v9
	v_cmp_ge_u32_e64 s[38:39], v162, v9
	v_cmp_ge_u32_e64 s[40:41], v161, v9
	v_cmp_ge_u32_e64 s[42:43], v164, v9
	v_cmp_ge_u32_e64 s[44:45], v163, v9
	v_cmp_ge_u32_e64 s[46:47], v166, v9
	v_cmp_ge_u32_e64 s[48:49], v165, v9
	v_cmp_ge_u32_e64 s[50:51], v168, v9
	v_addc_co_u32_e64 v10, s[66:67], 0, v10, s[36:37]
	v_addc_co_u32_e64 v11, s[68:69], 0, v11, s[38:39]
	v_addc_co_u32_e64 v10, s[66:67], 0, v10, s[40:41]
	v_addc_co_u32_e64 v11, s[68:69], 0, v11, s[42:43]
	v_addc_co_u32_e64 v10, s[66:67], 0, v10, s[44:45]
	v_addc_co_u32_e64 v11, s[68:69], 0, v11, s[46:47]
	v_addc_co_u32_e64 v10, s[66:67], 0, v10, s[48:49]
	v_addc_co_u32_e64 v11, s[68:69], 0, v11, s[50:51]
	v_cmp_ge_u32_e64 s[36:37], v167, v9
	v_cmp_ge_u32_e64 s[38:39], v170, v9
	v_cmp_ge_u32_e64 s[40:41], v169, v9
	v_cmp_ge_u32_e64 s[42:43], v172, v9
	v_cmp_ge_u32_e64 s[44:45], v171, v9
	v_cmp_ge_u32_e64 s[46:47], v174, v9
	v_cmp_ge_u32_e64 s[48:49], v173, v9
	v_cmp_ge_u32_e64 s[50:51], v182, v9
	v_addc_co_u32_e64 v10, s[66:67], 0, v10, s[36:37]
	v_addc_co_u32_e64 v11, s[68:69], 0, v11, s[38:39]
	v_addc_co_u32_e64 v10, s[66:67], 0, v10, s[40:41]
	v_addc_co_u32_e64 v11, s[68:69], 0, v11, s[42:43]
	v_addc_co_u32_e64 v10, s[66:67], 0, v10, s[44:45]
	v_addc_co_u32_e64 v11, s[68:69], 0, v11, s[46:47]
	v_addc_co_u32_e64 v10, s[66:67], 0, v10, s[48:49]
	v_addc_co_u32_e64 v11, s[68:69], 0, v11, s[50:51]
	v_cmp_ge_u32_e64 s[36:37], v175, v9
	v_cmp_ge_u32_e64 s[38:39], v184, v9
	v_cmp_ge_u32_e64 s[40:41], v183, v9
	v_cmp_ge_u32_e64 s[42:43], v186, v9
	v_cmp_ge_u32_e64 s[44:45], v185, v9
	v_cmp_ge_u32_e64 s[46:47], v188, v9
	v_cmp_ge_u32_e64 s[48:49], v187, v9
	v_cmp_ge_u32_e64 s[50:51], v190, v9
	v_addc_co_u32_e64 v10, s[66:67], 0, v10, s[36:37]
	v_addc_co_u32_e64 v11, s[68:69], 0, v11, s[38:39]
	v_addc_co_u32_e64 v10, s[66:67], 0, v10, s[40:41]
	v_addc_co_u32_e64 v11, s[68:69], 0, v11, s[42:43]
	v_addc_co_u32_e64 v10, s[66:67], 0, v10, s[44:45]
	v_addc_co_u32_e64 v11, s[68:69], 0, v11, s[46:47]
	v_addc_co_u32_e64 v10, s[66:67], 0, v10, s[48:49]
	v_addc_co_u32_e64 v11, s[68:69], 0, v11, s[50:51]
	v_cmp_ge_u32_e64 s[36:37], v189, v9
	v_cmp_ge_u32_e64 s[38:39], v192, v9
	v_cmp_ge_u32_e64 s[40:41], v191, v9
	v_cmp_ge_u32_e64 s[42:43], v194, v9
	v_cmp_ge_u32_e64 s[44:45], v193, v9
	v_cmp_ge_u32_e64 s[46:47], v196, v9
	v_cmp_ge_u32_e64 s[48:49], v195, v9
	v_cmp_ge_u32_e64 s[50:51], v198, v9
	v_addc_co_u32_e64 v10, s[66:67], 0, v10, s[36:37]
	v_addc_co_u32_e64 v11, s[68:69], 0, v11, s[38:39]
	v_addc_co_u32_e64 v10, s[66:67], 0, v10, s[40:41]
	v_addc_co_u32_e64 v11, s[68:69], 0, v11, s[42:43]
	v_addc_co_u32_e64 v10, s[66:67], 0, v10, s[44:45]
	v_addc_co_u32_e64 v11, s[68:69], 0, v11, s[46:47]
	v_addc_co_u32_e64 v10, s[66:67], 0, v10, s[48:49]
	v_addc_co_u32_e64 v11, s[68:69], 0, v11, s[50:51]
	v_cmp_ge_u32_e64 s[36:37], v197, v9
	v_cmp_ge_u32_e64 s[38:39], v200, v9
	v_cmp_ge_u32_e64 s[40:41], v199, v9
	v_cmp_ge_u32_e64 s[42:43], v202, v9
	v_cmp_ge_u32_e64 s[44:45], v201, v9
	v_cmp_ge_u32_e64 s[46:47], v204, v9
	v_cmp_ge_u32_e64 s[48:49], v203, v9
	v_cmp_ge_u32_e64 s[50:51], v206, v9
	v_addc_co_u32_e64 v10, s[66:67], 0, v10, s[36:37]
	v_addc_co_u32_e64 v11, s[68:69], 0, v11, s[38:39]
	v_addc_co_u32_e64 v10, s[66:67], 0, v10, s[40:41]
	v_addc_co_u32_e64 v11, s[68:69], 0, v11, s[42:43]
	v_addc_co_u32_e64 v10, s[66:67], 0, v10, s[44:45]
	v_addc_co_u32_e64 v11, s[68:69], 0, v11, s[46:47]
	v_addc_co_u32_e64 v10, s[66:67], 0, v10, s[48:49]
	v_addc_co_u32_e64 v11, s[68:69], 0, v11, s[50:51]
	v_cmp_ge_u32_e64 s[36:37], v205, v9
	v_cmp_ge_u32_e64 s[38:39], v236, v9
	v_cmp_ge_u32_e64 s[40:41], v207, v9
	v_cmp_ge_u32_e64 s[42:43], v238, v9
	v_cmp_ge_u32_e64 s[44:45], v237, v9
	v_cmp_ge_u32_e64 s[46:47], v240, v9
	v_cmp_ge_u32_e64 s[48:49], v239, v9
	v_cmp_ge_u32_e64 s[50:51], v18, v9
	v_addc_co_u32_e64 v10, s[66:67], 0, v10, s[36:37]
	v_addc_co_u32_e64 v11, s[68:69], 0, v11, s[38:39]
	v_addc_co_u32_e64 v10, s[66:67], 0, v10, s[40:41]
	v_addc_co_u32_e64 v11, s[68:69], 0, v11, s[42:43]
	v_addc_co_u32_e64 v10, s[66:67], 0, v10, s[44:45]
	v_addc_co_u32_e64 v11, s[68:69], 0, v11, s[46:47]
	v_addc_co_u32_e64 v10, s[66:67], 0, v10, s[48:49]
	v_addc_co_u32_e64 v11, s[68:69], 0, v11, s[50:51]
	v_add_u32_e32 v10, v10, v11
	ds_bpermute_b32 v11, v4, v10
	s_waitcnt lgkmcnt(0)
	v_add_u32_e32 v10, v10, v11
	s_nop 1
	v_add_u32_dpp v10, v10, v10 quad_perm:[1,0,3,2] row_mask:0xf bank_mask:0xf
	s_nop 1
	v_add_u32_dpp v10, v10, v10 quad_perm:[2,3,0,1] row_mask:0xf bank_mask:0xf
	s_nop 1
	v_add_u32_dpp v10, v10, v10 row_half_mirror row_mask:0xf bank_mask:0xf
	s_nop 1
	v_add_u32_dpp v10, v10, v10 row_mirror row_mask:0xf bank_mask:0xf
	v_cmp_gt_i32_e32 vcc, v10, v3
	s_nop 1
	v_cndmask_b32_e32 v144, v144, v9, vcc
	s_cbranch_scc0 .LBB0_974
; DI void indexer_phase(const u16* __restrict__ P, unsigned* __restrict__ mask) {
;     ...
;     unsigned w0 = 0u, w1 = 0u;
; #pragma unroll
;     for (int kb = 0; kb < 64; ++kb) {
;       const bool pred = (sc[kb] >= T) && (sc[kb] != 0u);
;       const unsigned long long bal = __ballot(pred);
;       const unsigned wd = (unsigned)(bal >> (32 * hi));
;       if ((kb & 31) == r32) { if (kb < 32) w0 = wd; else w1 = wd; }
;     }
	v_cmp_ge_u32_e32 vcc, v2, v144
	v_cmp_ne_u32_e64 s[0:1], 0, v2
	s_and_b64 s[0:1], s[0:1], vcc
	v_readlane_b32 s36, v254, 56
	v_cndmask_b32_e64 v2, 0, 1, s[0:1]
	v_cmp_ne_u32_e32 vcc, 0, v2
	v_cmp_ne_u32_e64 s[0:1], 0, v146
	v_readlane_b32 s37, v254, 57
	v_lshrrev_b64 v[2:3], v56, vcc
	v_cmp_ge_u32_e32 vcc, v146, v144
	s_and_b64 s[0:1], s[0:1], vcc
	v_cndmask_b32_e64 v4, 0, v2, s[36:37]
	v_cndmask_b32_e64 v2, 0, 1, s[0:1]
	v_cmp_ne_u32_e32 vcc, 0, v2
	v_readlane_b32 s38, v254, 58
	v_cmp_ne_u32_e64 s[0:1], 0, v145
	v_lshrrev_b64 v[2:3], v56, vcc
	v_cmp_ge_u32_e32 vcc, v145, v144
	v_readlane_b32 s39, v254, 59
	s_and_b64 s[0:1], s[0:1], vcc
	v_readlane_b32 s40, v254, 60
	v_cndmask_b32_e64 v4, v4, v2, s[38:39]
	v_cndmask_b32_e64 v2, 0, 1, s[0:1]
	v_cmp_ne_u32_e32 vcc, 0, v2
	v_cmp_ne_u32_e64 s[0:1], 0, v148
	v_readlane_b32 s41, v254, 61
	v_lshrrev_b64 v[2:3], v56, vcc
	v_cmp_ge_u32_e32 vcc, v148, v144
	s_and_b64 s[0:1], s[0:1], vcc
	v_cndmask_b32_e64 v4, v4, v2, s[40:41]
	v_cndmask_b32_e64 v2, 0, 1, s[0:1]
	v_cmp_ne_u32_e32 vcc, 0, v2
	v_readlane_b32 s44, v254, 62
	v_cmp_ne_u32_e64 s[0:1], 0, v147
	v_lshrrev_b64 v[2:3], v56, vcc
	v_cmp_ge_u32_e32 vcc, v147, v144
	v_readlane_b32 s45, v254, 63
	s_and_b64 s[0:1], s[0:1], vcc
	v_readlane_b32 s46, v255, 0
	v_cndmask_b32_e64 v4, v4, v2, s[44:45]
	v_cndmask_b32_e64 v2, 0, 1, s[0:1]
	v_cmp_ne_u32_e32 vcc, 0, v2
	v_cmp_ne_u32_e64 s[0:1], 0, v150
	v_readlane_b32 s47, v255, 1
	v_lshrrev_b64 v[2:3], v56, vcc
	v_cmp_ge_u32_e32 vcc, v150, v144
	s_and_b64 s[0:1], s[0:1], vcc
	v_cndmask_b32_e64 v4, v4, v2, s[46:47]
	v_cndmask_b32_e64 v2, 0, 1, s[0:1]
	v_cmp_ne_u32_e32 vcc, 0, v2
	v_readlane_b32 s48, v255, 2
	v_cmp_ne_u32_e64 s[0:1], 0, v149
	v_lshrrev_b64 v[2:3], v56, vcc
	v_cmp_ge_u32_e32 vcc, v149, v144
	v_readlane_b32 s49, v255, 3
	s_and_b64 s[0:1], s[0:1], vcc
	v_readlane_b32 s50, v255, 4
	v_cndmask_b32_e64 v4, v4, v2, s[48:49]
	v_cndmask_b32_e64 v2, 0, 1, s[0:1]
	v_cmp_ne_u32_e32 vcc, 0, v2
	v_cmp_ne_u32_e64 s[0:1], 0, v152
	v_readlane_b32 s51, v255, 5
	v_lshrrev_b64 v[2:3], v56, vcc
	v_cmp_ge_u32_e32 vcc, v152, v144
	s_and_b64 s[0:1], s[0:1], vcc
	v_cndmask_b32_e64 v4, v4, v2, s[50:51]
	v_cndmask_b32_e64 v2, 0, 1, s[0:1]
	v_cmp_ne_u32_e32 vcc, 0, v2
	v_readlane_b32 s18, v255, 6
	v_cmp_ne_u32_e64 s[0:1], 0, v151
	v_lshrrev_b64 v[2:3], v56, vcc
	v_cmp_ge_u32_e32 vcc, v151, v144
	v_readlane_b32 s19, v255, 7
	s_and_b64 s[0:1], s[0:1], vcc
	v_readlane_b32 s22, v255, 8
	v_cndmask_b32_e64 v4, v4, v2, s[18:19]
	v_cndmask_b32_e64 v2, 0, 1, s[0:1]
	v_cmp_ne_u32_e32 vcc, 0, v2
	v_cmp_ne_u32_e64 s[0:1], 0, v154
	v_readlane_b32 s23, v255, 9
	v_lshrrev_b64 v[2:3], v56, vcc
	v_cmp_ge_u32_e32 vcc, v154, v144
	s_and_b64 s[0:1], s[0:1], vcc
	v_cndmask_b32_e64 v4, v4, v2, s[22:23]
	v_cndmask_b32_e64 v2, 0, 1, s[0:1]
	v_cmp_ne_u32_e32 vcc, 0, v2
	v_readlane_b32 s24, v255, 10
	v_cmp_ne_u32_e64 s[0:1], 0, v153
	v_lshrrev_b64 v[2:3], v56, vcc
	v_cmp_ge_u32_e32 vcc, v153, v144
	v_readlane_b32 s25, v255, 11
	s_and_b64 s[0:1], s[0:1], vcc
	v_readlane_b32 s26, v255, 12
	v_cndmask_b32_e64 v4, v4, v2, s[24:25]
	v_cndmask_b32_e64 v2, 0, 1, s[0:1]
	v_cmp_ne_u32_e32 vcc, 0, v2
	v_cmp_ne_u32_e64 s[0:1], 0, v156
	v_readlane_b32 s27, v255, 13
	v_lshrrev_b64 v[2:3], v56, vcc
	v_cmp_ge_u32_e32 vcc, v156, v144
	s_and_b64 s[0:1], s[0:1], vcc
	v_cndmask_b32_e64 v4, v4, v2, s[26:27]
	v_cndmask_b32_e64 v2, 0, 1, s[0:1]
	v_cmp_ne_u32_e32 vcc, 0, v2
	v_readlane_b32 s30, v255, 14
	v_cmp_ne_u32_e64 s[0:1], 0, v155
	v_lshrrev_b64 v[2:3], v56, vcc
	v_cmp_ge_u32_e32 vcc, v155, v144
	v_readlane_b32 s31, v255, 15
	s_and_b64 s[0:1], s[0:1], vcc
	v_readlane_b32 s8, v255, 16
	v_cndmask_b32_e64 v4, v4, v2, s[30:31]
	v_cndmask_b32_e64 v2, 0, 1, s[0:1]
	v_cmp_ne_u32_e32 vcc, 0, v2
	v_cmp_ne_u32_e64 s[0:1], 0, v158
	v_readlane_b32 s9, v255, 17
	v_lshrrev_b64 v[2:3], v56, vcc
	v_cmp_ge_u32_e32 vcc, v158, v144
	s_and_b64 s[0:1], s[0:1], vcc
	v_cndmask_b32_e64 v4, v4, v2, s[8:9]
	v_cndmask_b32_e64 v2, 0, 1, s[0:1]
	v_cmp_ne_u32_e32 vcc, 0, v2
	v_readlane_b32 s10, v255, 18
	v_cmp_ne_u32_e64 s[0:1], 0, v157
	v_lshrrev_b64 v[2:3], v56, vcc
	v_cmp_ge_u32_e32 vcc, v157, v144
	v_readlane_b32 s11, v255, 19
	s_and_b64 s[0:1], s[0:1], vcc
	v_readlane_b32 s12, v255, 20
	v_cndmask_b32_e64 v4, v4, v2, s[10:11]
	v_cndmask_b32_e64 v2, 0, 1, s[0:1]
	v_cmp_ne_u32_e32 vcc, 0, v2
	v_cmp_ne_u32_e64 s[0:1], 0, v160
	v_readlane_b32 s13, v255, 21
	v_lshrrev_b64 v[2:3], v56, vcc
	v_cmp_ge_u32_e32 vcc, v160, v144
	s_and_b64 s[0:1], s[0:1], vcc
	v_cndmask_b32_e64 v4, v4, v2, s[12:13]
	v_cndmask_b32_e64 v2, 0, 1, s[0:1]
	v_cmp_ne_u32_e32 vcc, 0, v2
	v_readlane_b32 s14, v255, 22
	v_cmp_ne_u32_e64 s[0:1], 0, v159
	v_lshrrev_b64 v[2:3], v56, vcc
	v_cmp_ge_u32_e32 vcc, v159, v144
	v_readlane_b32 s15, v255, 23
	s_and_b64 s[0:1], s[0:1], vcc
	v_readlane_b32 s66, v255, 24
	v_cndmask_b32_e64 v4, v4, v2, s[14:15]
	v_cndmask_b32_e64 v2, 0, 1, s[0:1]
	v_cmp_ne_u32_e32 vcc, 0, v2
	v_cmp_ne_u32_e64 s[0:1], 0, v162
	v_readlane_b32 s67, v255, 25
	v_lshrrev_b64 v[2:3], v56, vcc
	v_cmp_ge_u32_e32 vcc, v162, v144
	s_and_b64 s[0:1], s[0:1], vcc
	v_cndmask_b32_e64 v4, v4, v2, s[66:67]
	v_cndmask_b32_e64 v2, 0, 1, s[0:1]
	v_cmp_ne_u32_e32 vcc, 0, v2
	v_readlane_b32 s68, v255, 26
	v_cmp_ne_u32_e64 s[0:1], 0, v161
	v_lshrrev_b64 v[2:3], v56, vcc
	v_cmp_ge_u32_e32 vcc, v161, v144
	v_readlane_b32 s69, v255, 27
	s_and_b64 s[0:1], s[0:1], vcc
	v_readlane_b32 s70, v255, 28
	v_cndmask_b32_e64 v4, v4, v2, s[68:69]
	v_cndmask_b32_e64 v2, 0, 1, s[0:1]
	v_cmp_ne_u32_e32 vcc, 0, v2
	v_cmp_ne_u32_e64 s[0:1], 0, v164
	v_readlane_b32 s71, v255, 29
	v_lshrrev_b64 v[2:3], v56, vcc
	v_cmp_ge_u32_e32 vcc, v164, v144
; DI void indexer_phase(const u16* __restrict__ P, unsigned* __restrict__ mask) {
;     ...
;     unsigned w0 = 0u, w1 = 0u;
; #pragma unroll
;     for (int kb = 0; kb < 64; ++kb) {
;       const bool pred = (sc[kb] >= T) && (sc[kb] != 0u);
;       const unsigned long long bal = __ballot(pred);
;       const unsigned wd = (unsigned)(bal >> (32 * hi));
;       if ((kb & 31) == r32) { if (kb < 32) w0 = wd; else w1 = wd; }
;     }
	s_and_b64 s[0:1], s[0:1], vcc
	v_cndmask_b32_e64 v4, v4, v2, s[70:71]
	v_cndmask_b32_e64 v2, 0, 1, s[0:1]
	v_cmp_ne_u32_e32 vcc, 0, v2
	v_readlane_b32 s72, v255, 30
	v_cmp_ne_u32_e64 s[0:1], 0, v163
	v_lshrrev_b64 v[2:3], v56, vcc
	v_cmp_ge_u32_e32 vcc, v163, v144
	v_readlane_b32 s73, v255, 31
	s_and_b64 s[0:1], s[0:1], vcc
	v_readlane_b32 s42, v255, 32
	v_cndmask_b32_e64 v4, v4, v2, s[72:73]
	v_cndmask_b32_e64 v2, 0, 1, s[0:1]
	v_cmp_ne_u32_e32 vcc, 0, v2
	v_cmp_ne_u32_e64 s[0:1], 0, v166
	v_readlane_b32 s43, v255, 33
	v_lshrrev_b64 v[2:3], v56, vcc
	v_cmp_ge_u32_e32 vcc, v166, v144
	s_and_b64 s[0:1], s[0:1], vcc
	v_cndmask_b32_e64 v4, v4, v2, s[42:43]
	v_cndmask_b32_e64 v2, 0, 1, s[0:1]
	v_cmp_ne_u32_e32 vcc, 0, v2
	v_readlane_b32 s34, v255, 34
	v_cmp_ne_u32_e64 s[0:1], 0, v165
	v_lshrrev_b64 v[2:3], v56, vcc
	v_cmp_ge_u32_e32 vcc, v165, v144
	v_readlane_b32 s35, v255, 35
	s_and_b64 s[0:1], s[0:1], vcc
	v_readlane_b32 s52, v255, 36
	v_cndmask_b32_e64 v4, v4, v2, s[34:35]
	v_cndmask_b32_e64 v2, 0, 1, s[0:1]
	v_cmp_ne_u32_e32 vcc, 0, v2
	v_cmp_ne_u32_e64 s[0:1], 0, v168
	v_readlane_b32 s53, v255, 37
	v_lshrrev_b64 v[2:3], v56, vcc
	v_cmp_ge_u32_e32 vcc, v168, v144
	s_and_b64 s[0:1], s[0:1], vcc
	v_cndmask_b32_e64 v4, v4, v2, s[52:53]
	v_cndmask_b32_e64 v2, 0, 1, s[0:1]
	v_cmp_ne_u32_e32 vcc, 0, v2
	v_readlane_b32 s90, v255, 38
	v_cmp_ne_u32_e64 s[0:1], 0, v167
	v_lshrrev_b64 v[2:3], v56, vcc
	v_cmp_ge_u32_e32 vcc, v167, v144
	v_readlane_b32 s91, v255, 39
	s_and_b64 s[0:1], s[0:1], vcc
	v_readlane_b32 s28, v255, 40
	v_cndmask_b32_e64 v4, v4, v2, s[90:91]
	v_cndmask_b32_e64 v2, 0, 1, s[0:1]
	v_cmp_ne_u32_e32 vcc, 0, v2
	v_cmp_ne_u32_e64 s[0:1], 0, v170
	v_readlane_b32 s29, v255, 41
	v_lshrrev_b64 v[2:3], v56, vcc
	v_cmp_ge_u32_e32 vcc, v170, v144
	s_and_b64 s[0:1], s[0:1], vcc
	v_cndmask_b32_e64 v4, v4, v2, s[28:29]
	v_cndmask_b32_e64 v2, 0, 1, s[0:1]
	v_cmp_ne_u32_e32 vcc, 0, v2
	v_readlane_b32 s54, v255, 42
	v_cmp_ne_u32_e64 s[0:1], 0, v169
	v_lshrrev_b64 v[2:3], v56, vcc
	v_cmp_ge_u32_e32 vcc, v169, v144
	v_readlane_b32 s55, v255, 43
	s_and_b64 s[0:1], s[0:1], vcc
	v_readlane_b32 s94, v255, 44
	v_cndmask_b32_e64 v4, v4, v2, s[54:55]
	v_cndmask_b32_e64 v2, 0, 1, s[0:1]
	v_cmp_ne_u32_e32 vcc, 0, v2
	v_cmp_ne_u32_e64 s[0:1], 0, v172
	v_readlane_b32 s95, v255, 45
	v_lshrrev_b64 v[2:3], v56, vcc
	v_cmp_ge_u32_e32 vcc, v172, v144
	s_and_b64 s[0:1], s[0:1], vcc
	v_cndmask_b32_e64 v4, v4, v2, s[94:95]
	v_cndmask_b32_e64 v2, 0, 1, s[0:1]
	v_cmp_ne_u32_e32 vcc, 0, v2
	v_readlane_b32 s2, v255, 46
	v_cmp_ne_u32_e64 s[0:1], 0, v171
	v_lshrrev_b64 v[2:3], v56, vcc
	v_cmp_ge_u32_e32 vcc, v171, v144
	v_readlane_b32 s3, v255, 47
	s_and_b64 s[0:1], s[0:1], vcc
	v_readlane_b32 s4, v255, 48
	v_cndmask_b32_e64 v4, v4, v2, s[2:3]
	v_cndmask_b32_e64 v2, 0, 1, s[0:1]
	v_cmp_ne_u32_e32 vcc, 0, v2
	v_cmp_ne_u32_e64 s[0:1], 0, v174
	v_readlane_b32 s5, v255, 49
	v_lshrrev_b64 v[2:3], v56, vcc
	v_cmp_ge_u32_e32 vcc, v174, v144
	s_and_b64 s[0:1], s[0:1], vcc
	v_cndmask_b32_e64 v4, v4, v2, s[4:5]
	v_cndmask_b32_e64 v2, 0, 1, s[0:1]
	v_cmp_ne_u32_e32 vcc, 0, v2
	v_readlane_b32 s20, v255, 50
	v_cmp_ne_u32_e64 s[0:1], 0, v173
	v_lshrrev_b64 v[2:3], v56, vcc
	v_cmp_ge_u32_e32 vcc, v173, v144
	v_readlane_b32 s21, v255, 51
	s_and_b64 s[0:1], s[0:1], vcc
	v_readlane_b32 s64, v255, 52
	v_cndmask_b32_e64 v4, v4, v2, s[20:21]
	v_cndmask_b32_e64 v2, 0, 1, s[0:1]
	v_cmp_ne_u32_e32 vcc, 0, v2
	v_cmp_ne_u32_e64 s[0:1], 0, v182
	v_readlane_b32 s65, v255, 53
	v_lshrrev_b64 v[2:3], v56, vcc
	v_cmp_ge_u32_e32 vcc, v182, v144
	s_and_b64 s[0:1], s[0:1], vcc
	v_cndmask_b32_e64 v4, v4, v2, s[64:65]
	v_cndmask_b32_e64 v2, 0, 1, s[0:1]
	v_cmp_ne_u32_e32 vcc, 0, v2
	v_readlane_b32 s74, v255, 54
	v_cmp_ne_u32_e64 s[0:1], 0, v175
	v_lshrrev_b64 v[2:3], v56, vcc
	v_cmp_ge_u32_e32 vcc, v175, v144
	v_readlane_b32 s75, v255, 55
	s_and_b64 s[0:1], s[0:1], vcc
	s_nop 0
	v_cndmask_b32_e64 v4, v4, v2, s[74:75]
	v_cndmask_b32_e64 v2, 0, 1, s[0:1]
	v_cmp_ne_u32_e32 vcc, 0, v2
	v_cmp_ne_u32_e64 s[0:1], 0, v184
	s_nop 0
	v_lshrrev_b64 v[2:3], v56, vcc
	v_cmp_ge_u32_e32 vcc, v184, v144
	s_and_b64 s[0:1], s[0:1], vcc
	v_cndmask_b32_e64 v5, 0, v2, s[36:37]
	v_cndmask_b32_e64 v2, 0, 1, s[0:1]
	v_cmp_ne_u32_e32 vcc, 0, v2
	v_cmp_ne_u32_e64 s[0:1], 0, v183
	s_nop 0
	v_lshrrev_b64 v[2:3], v56, vcc
	v_cmp_ge_u32_e32 vcc, v183, v144
	s_and_b64 s[0:1], s[0:1], vcc
	v_cndmask_b32_e64 v5, v5, v2, s[38:39]
	v_cndmask_b32_e64 v2, 0, 1, s[0:1]
	v_cmp_ne_u32_e32 vcc, 0, v2
	v_cmp_ne_u32_e64 s[0:1], 0, v186
	s_nop 0
	v_lshrrev_b64 v[2:3], v56, vcc
	v_cmp_ge_u32_e32 vcc, v186, v144
	s_and_b64 s[0:1], s[0:1], vcc
	v_cndmask_b32_e64 v5, v5, v2, s[40:41]
	v_cndmask_b32_e64 v2, 0, 1, s[0:1]
	v_cmp_ne_u32_e32 vcc, 0, v2
	v_cmp_ne_u32_e64 s[0:1], 0, v185
	s_nop 0
	v_lshrrev_b64 v[2:3], v56, vcc
	v_cmp_ge_u32_e32 vcc, v185, v144
	s_and_b64 s[0:1], s[0:1], vcc
	v_cndmask_b32_e64 v5, v5, v2, s[44:45]
	v_cndmask_b32_e64 v2, 0, 1, s[0:1]
	v_cmp_ne_u32_e32 vcc, 0, v2
	v_cmp_ne_u32_e64 s[0:1], 0, v188
	s_nop 0
	v_lshrrev_b64 v[2:3], v56, vcc
	v_cmp_ge_u32_e32 vcc, v188, v144
	s_and_b64 s[0:1], s[0:1], vcc
	v_cndmask_b32_e64 v5, v5, v2, s[46:47]
	v_cndmask_b32_e64 v2, 0, 1, s[0:1]
	v_cmp_ne_u32_e32 vcc, 0, v2
	v_cmp_ne_u32_e64 s[0:1], 0, v187
	s_nop 0
	v_lshrrev_b64 v[2:3], v56, vcc
	v_cmp_ge_u32_e32 vcc, v187, v144
	s_and_b64 s[0:1], s[0:1], vcc
	v_cndmask_b32_e64 v5, v5, v2, s[48:49]
	v_cndmask_b32_e64 v2, 0, 1, s[0:1]
	v_cmp_ne_u32_e32 vcc, 0, v2
	v_cmp_ne_u32_e64 s[0:1], 0, v190
	s_nop 0
	v_lshrrev_b64 v[2:3], v56, vcc
	v_cmp_ge_u32_e32 vcc, v190, v144
	s_and_b64 s[0:1], s[0:1], vcc
	v_cndmask_b32_e64 v5, v5, v2, s[50:51]
; DI void indexer_phase(const u16* __restrict__ P, unsigned* __restrict__ mask) {
;     ...
;     unsigned w0 = 0u, w1 = 0u;
; #pragma unroll
;     for (int kb = 0; kb < 64; ++kb) {
;       const bool pred = (sc[kb] >= T) && (sc[kb] != 0u);
;       const unsigned long long bal = __ballot(pred);
;       const unsigned wd = (unsigned)(bal >> (32 * hi));
;       if ((kb & 31) == r32) { if (kb < 32) w0 = wd; else w1 = wd; }
;     }
;     mask[(brow + tme) * 64 + r32] = w0;
;     mask[(brow + tme) * 64 + 32 + r32] = w1;
	v_cndmask_b32_e64 v2, 0, 1, s[0:1]
	v_cmp_ne_u32_e32 vcc, 0, v2
	v_cmp_ne_u32_e64 s[0:1], 0, v189
	s_nop 0
	v_lshrrev_b64 v[2:3], v56, vcc
	v_cmp_ge_u32_e32 vcc, v189, v144
	s_and_b64 s[0:1], s[0:1], vcc
	v_cndmask_b32_e64 v5, v5, v2, s[18:19]
	v_cndmask_b32_e64 v2, 0, 1, s[0:1]
	v_cmp_ne_u32_e32 vcc, 0, v2
	v_cmp_ne_u32_e64 s[0:1], 0, v192
	s_nop 0
	v_lshrrev_b64 v[2:3], v56, vcc
	v_cmp_ge_u32_e32 vcc, v192, v144
	s_and_b64 s[0:1], s[0:1], vcc
	v_cndmask_b32_e64 v5, v5, v2, s[22:23]
	v_cndmask_b32_e64 v2, 0, 1, s[0:1]
	v_cmp_ne_u32_e32 vcc, 0, v2
	v_cmp_ne_u32_e64 s[0:1], 0, v191
	s_nop 0
	v_lshrrev_b64 v[2:3], v56, vcc
	v_cmp_ge_u32_e32 vcc, v191, v144
	s_and_b64 s[0:1], s[0:1], vcc
	v_cndmask_b32_e64 v5, v5, v2, s[24:25]
	v_cndmask_b32_e64 v2, 0, 1, s[0:1]
	v_cmp_ne_u32_e32 vcc, 0, v2
	v_cmp_ne_u32_e64 s[0:1], 0, v194
	s_nop 0
	v_lshrrev_b64 v[2:3], v56, vcc
	v_cmp_ge_u32_e32 vcc, v194, v144
	s_and_b64 s[0:1], s[0:1], vcc
	v_cndmask_b32_e64 v5, v5, v2, s[26:27]
	v_cndmask_b32_e64 v2, 0, 1, s[0:1]
	v_cmp_ne_u32_e32 vcc, 0, v2
	v_cmp_ne_u32_e64 s[0:1], 0, v193
	s_nop 0
	v_lshrrev_b64 v[2:3], v56, vcc
	v_cmp_ge_u32_e32 vcc, v193, v144
	s_and_b64 s[0:1], s[0:1], vcc
	v_cndmask_b32_e64 v5, v5, v2, s[30:31]
	v_cndmask_b32_e64 v2, 0, 1, s[0:1]
	v_cmp_ne_u32_e32 vcc, 0, v2
	v_cmp_ne_u32_e64 s[0:1], 0, v196
	s_nop 0
	v_lshrrev_b64 v[2:3], v56, vcc
	v_cmp_ge_u32_e32 vcc, v196, v144
	s_and_b64 s[0:1], s[0:1], vcc
	v_cndmask_b32_e64 v5, v5, v2, s[8:9]
	v_cndmask_b32_e64 v2, 0, 1, s[0:1]
	v_cmp_ne_u32_e32 vcc, 0, v2
	v_cmp_ne_u32_e64 s[0:1], 0, v195
	v_readlane_b32 s8, v255, 56
	v_lshrrev_b64 v[2:3], v56, vcc
	v_cmp_ge_u32_e32 vcc, v195, v144
	s_and_b64 s[0:1], s[0:1], vcc
	v_cndmask_b32_e64 v5, v5, v2, s[10:11]
	v_cndmask_b32_e64 v2, 0, 1, s[0:1]
	v_cmp_ne_u32_e32 vcc, 0, v2
	v_cmp_ne_u32_e64 s[0:1], 0, v198
	v_readlane_b32 s9, v255, 57
	v_lshrrev_b64 v[2:3], v56, vcc
	v_cmp_ge_u32_e32 vcc, v198, v144
	s_and_b64 s[0:1], s[0:1], vcc
	v_cndmask_b32_e64 v5, v5, v2, s[12:13]
	v_cndmask_b32_e64 v2, 0, 1, s[0:1]
	v_cmp_ne_u32_e32 vcc, 0, v2
	v_cmp_ne_u32_e64 s[0:1], 0, v197
	s_nop 0
	v_lshrrev_b64 v[2:3], v56, vcc
	v_cmp_ge_u32_e32 vcc, v197, v144
	s_and_b64 s[0:1], s[0:1], vcc
	v_cndmask_b32_e64 v5, v5, v2, s[14:15]
	v_cndmask_b32_e64 v2, 0, 1, s[0:1]
	v_cmp_ne_u32_e32 vcc, 0, v2
	v_cmp_ne_u32_e64 s[0:1], 0, v200
	s_nop 0
	v_lshrrev_b64 v[2:3], v56, vcc
	v_cmp_ge_u32_e32 vcc, v200, v144
	s_and_b64 s[0:1], s[0:1], vcc
	v_cndmask_b32_e64 v5, v5, v2, s[66:67]
	v_cndmask_b32_e64 v2, 0, 1, s[0:1]
	v_cmp_ne_u32_e32 vcc, 0, v2
	v_cmp_ne_u32_e64 s[0:1], 0, v199
	s_nop 0
	v_lshrrev_b64 v[2:3], v56, vcc
	v_cmp_ge_u32_e32 vcc, v199, v144
	s_and_b64 s[0:1], s[0:1], vcc
	v_cndmask_b32_e64 v5, v5, v2, s[68:69]
	v_cndmask_b32_e64 v2, 0, 1, s[0:1]
	v_cmp_ne_u32_e32 vcc, 0, v2
	v_cmp_ne_u32_e64 s[0:1], 0, v202
	s_nop 0
	v_lshrrev_b64 v[2:3], v56, vcc
	v_cmp_ge_u32_e32 vcc, v202, v144
	s_and_b64 s[0:1], s[0:1], vcc
	v_cndmask_b32_e64 v5, v5, v2, s[70:71]
	v_cndmask_b32_e64 v2, 0, 1, s[0:1]
	v_cmp_ne_u32_e32 vcc, 0, v2
	v_cmp_ne_u32_e64 s[0:1], 0, v201
	s_nop 0
	v_lshrrev_b64 v[2:3], v56, vcc
	v_cmp_ge_u32_e32 vcc, v201, v144
	s_and_b64 s[0:1], s[0:1], vcc
	v_cndmask_b32_e64 v5, v5, v2, s[72:73]
	v_cndmask_b32_e64 v2, 0, 1, s[0:1]
	v_cmp_ne_u32_e32 vcc, 0, v2
	v_cmp_ne_u32_e64 s[0:1], 0, v204
	s_nop 0
	v_lshrrev_b64 v[2:3], v56, vcc
	v_cmp_ge_u32_e32 vcc, v204, v144
	s_and_b64 s[0:1], s[0:1], vcc
	v_cndmask_b32_e64 v5, v5, v2, s[42:43]
	v_cndmask_b32_e64 v2, 0, 1, s[0:1]
	v_cmp_ne_u32_e32 vcc, 0, v2
	v_cmp_ne_u32_e64 s[0:1], 0, v203
	s_mov_b64 s[42:43], s[76:77]
	v_lshrrev_b64 v[2:3], v56, vcc
	v_cmp_ge_u32_e32 vcc, v203, v144
	s_and_b64 s[0:1], s[0:1], vcc
	v_cndmask_b32_e64 v5, v5, v2, s[34:35]
	v_cndmask_b32_e64 v2, 0, 1, s[0:1]
	v_cmp_ne_u32_e32 vcc, 0, v2
	v_cmp_ne_u32_e64 s[0:1], 0, v206
	v_readlane_b32 s76, v254, 37
	v_lshrrev_b64 v[2:3], v56, vcc
	v_cmp_ge_u32_e32 vcc, v206, v144
	s_and_b64 s[0:1], s[0:1], vcc
	v_cndmask_b32_e64 v5, v5, v2, s[52:53]
	v_cndmask_b32_e64 v2, 0, 1, s[0:1]
	v_cmp_ne_u32_e32 vcc, 0, v2
	v_cmp_ne_u32_e64 s[0:1], 0, v205
	s_mov_b64 s[52:53], s[96:97]
	v_lshrrev_b64 v[2:3], v56, vcc
	v_cmp_ge_u32_e32 vcc, v205, v144
	s_and_b64 s[0:1], s[0:1], vcc
	v_cndmask_b32_e64 v5, v5, v2, s[90:91]
	v_cndmask_b32_e64 v2, 0, 1, s[0:1]
	v_cmp_ne_u32_e32 vcc, 0, v2
	v_cmp_ne_u32_e64 s[0:1], 0, v236
	v_readlane_b32 s96, v254, 33
	v_lshrrev_b64 v[2:3], v56, vcc
	v_cmp_ge_u32_e32 vcc, v236, v144
	s_and_b64 s[0:1], s[0:1], vcc
	v_cndmask_b32_e64 v5, v5, v2, s[28:29]
	v_cndmask_b32_e64 v2, 0, 1, s[0:1]
	v_cmp_ne_u32_e32 vcc, 0, v2
	v_cmp_ne_u32_e64 s[0:1], 0, v207
	v_readlane_b32 s77, v254, 38
	v_lshrrev_b64 v[2:3], v56, vcc
	v_cmp_ge_u32_e32 vcc, v207, v144
	s_and_b64 s[0:1], s[0:1], vcc
	v_cndmask_b32_e64 v5, v5, v2, s[54:55]
	v_cndmask_b32_e64 v2, 0, 1, s[0:1]
	v_cmp_ne_u32_e32 vcc, 0, v2
	v_cmp_ne_u32_e64 s[0:1], 0, v238
	s_movk_i32 s34, 0xc00
	v_lshrrev_b64 v[2:3], v56, vcc
	v_cmp_ge_u32_e32 vcc, v238, v144
	s_and_b64 s[0:1], s[0:1], vcc
	v_cndmask_b32_e64 v5, v5, v2, s[94:95]
	v_cndmask_b32_e64 v2, 0, 1, s[0:1]
	v_cmp_ne_u32_e32 vcc, 0, v2
	v_cmp_ne_u32_e64 s[0:1], 0, v237
	s_mov_b64 s[90:91], s[16:17]
	v_lshrrev_b64 v[2:3], v56, vcc
	v_cmp_ge_u32_e32 vcc, v237, v144
	s_and_b64 s[0:1], s[0:1], vcc
	v_cndmask_b32_e64 v5, v5, v2, s[2:3]
	v_cndmask_b32_e64 v2, 0, 1, s[0:1]
	v_cmp_ne_u32_e32 vcc, 0, v2
	v_cmp_ne_u32_e64 s[0:1], 0, v240
	s_mov_b32 s28, s78
	v_lshrrev_b64 v[2:3], v56, vcc
	v_cmp_ge_u32_e32 vcc, v240, v144
	s_and_b64 s[0:1], s[0:1], vcc
	v_cndmask_b32_e64 v5, v5, v2, s[4:5]
	v_cndmask_b32_e64 v2, 0, 1, s[0:1]
	v_cmp_ne_u32_e32 vcc, 0, v2
	v_cmp_ne_u32_e64 s[0:1], 0, v239
	s_mov_b64 s[4:5], s[84:85]
	v_lshrrev_b64 v[2:3], v56, vcc
	v_cmp_ge_u32_e32 vcc, v239, v144
	s_and_b64 s[0:1], s[0:1], vcc
	v_cndmask_b32_e64 v5, v5, v2, s[20:21]
	v_cndmask_b32_e64 v2, 0, 1, s[0:1]
	v_cmp_ne_u32_e32 vcc, 0, v2
	v_cmp_ne_u32_e64 s[0:1], 0, v18
	v_readlane_b32 s97, v254, 34
	v_lshrrev_b64 v[2:3], v56, vcc
	v_cmp_ge_u32_e32 vcc, v18, v144
	s_and_b64 s[0:1], s[0:1], vcc
	v_cndmask_b32_e64 v5, v5, v2, s[64:65]
	v_cndmask_b32_e64 v2, 0, 1, s[0:1]
	v_cmp_ne_u32_e32 vcc, 0, v2
	s_mov_b32 s35, s86
	s_mov_b32 s84, s79
	v_lshrrev_b64 v[2:3], v56, vcc
	v_cndmask_b32_e64 v5, v5, v2, s[74:75]
	v_add_u32_e32 v2, v127, v126
	v_mov_b32_e32 v3, v1
	v_lshlrev_b64 v[2:3], 8, v[2:3]
	v_readlane_b32 s74, v254, 35
	v_lshl_add_u64 v[2:3], v[58:59], 0, v[2:3]
	v_readlane_b32 s75, v254, 36
	s_mov_b32 s55, s59
	s_mov_b32 s3, s63
	s_movk_i32 s20, 0x600
	s_mov_b32 s21, 0x41000000
	s_mov_b32 s64, 0x3e38aa3b
	s_movk_i32 s2, 0x2000
	global_store_dword v[2:3], v4, off
	global_store_dword v[2:3], v5, off offset:128
	s_branch .LBB0_845

; template <int DQK, int W1, int DV, int VW, int MODE> ...
;     ...
;   auto stage_tile = [&](int kb, int buf) {
;     const unsigned bofs = (unsigned)(buf * BUF);
;     if (MODE != 2) {
; #pragma unroll
;       for (int ii = 0; ii < NKS; ++ii) {
;         const int i = wv + 8 * ii;
;         if (i < NKI) { __builtin_amdgcn_global_load_lds((const unsigned*)kptr[ii], (lds_u32p)(smem + bofs + i * 1024), 16, 0, 0); kptr[ii] += kstr[ii]; }
;       }
; #pragma unroll
;       for (int ii = 0; ii < NVS; ++ii) {
;         const int i = wv + 8 * ii;
;         if (i < NVI) { __builtin_amdgcn_global_load_lds((const unsigned*)vptr[ii], (lds_u32p)(smem + bofs + 64 * KSTR + i * 1024), 16, 0, 0); vptr[ii] += 64 * ldv; }
;       }
;     } else {
;       int ln = threadIdx.x & 63; asm volatile("" : "+v"(ln));
; #pragma unroll
;       for (int ii = 0; ii < NKS; ++ii) {
;         const int i = wv + 8 * ii;
;         if (i < NKI) {
;           const int ob = i * 1024 + ln * 16, row = ob / KSTR;
;           int c = (ob - row * KSTR) >> 4; c = (c >= KCH) ? 0 : c;
;           int key = kb + row; key = key < 0 ? 0 : (key >= kv_len ? kv_len - 1 : key);
;           const u16* src = (c < W1 / 8) ? (k1 + (key * ldk1 + c * 8)) : (k2 + (key * ldk2 + (c - W1 / 8) * 8));
;           __builtin_amdgcn_global_load_lds((const unsigned*)src, (lds_u32p)(smem + bofs + i * 1024), 16, 0, 0);
;         }
;       }
; #pragma unroll
;       for (int ii = 0; ii < NVS; ++ii) {
;         const int i = wv + 8 * ii;
;         if (i < NVI) {
;           const int ob = i * 1024 + ln * 16, cbk = ob >> 12, row = (ob & 4095) >> 6, cw = (ob & 63) >> 4;
;           int key = kb + row; key = key < 0 ? 0 : (key >= kv_len ? kv_len - 1 : key);
;           __builtin_amdgcn_global_load_lds((const unsigned*)(vsrc + (key * ldv + (cbk * 4 + cw) * 8)), (lds_u32p)(smem + bofs + 64 * KSTR + i * 1024), 16, 0, 0);
;         }
;       }
;     }
;     if (MODE == 1) { mwn[0] = maskrow[(kb >> 5)]; mwn[1] = maskrow[(kb >> 5) + 1]; }
;   };
;   stage_tile(kbase0, 0);
;   asm volatile("s_waitcnt vmcnt(0)" ::: "memory");
;   __syncthreads();
;   for (int t = 0; t < ntiles; ++t) {
;     const int kb = kbase0 + t * 64;
;     const unsigned bufa = lds0 + (unsigned)((t & 1) * BUF);
;     const unsigned mw0 = mwn[0], mw1 = mwn[1];
;     if (t + 1 < ntiles) stage_tile(kb + 64, (t + 1) & 1);
.LBB0_1327:
	v_readlane_b32 s0, v250, 46
	v_lshlrev_b64 v[4:5], 8, v[86:87]
	v_readlane_b32 s1, v250, 47
	v_and_b32_e32 v0, 31, v3
	v_lshlrev_b32_e32 v82, 2, v2
	v_lshl_add_u64 v[96:97], s[0:1], 0, v[4:5]
	global_load_dwordx2 v[116:117], v[96:97], off
	v_lshlrev_b32_e32 v4, 1, v3
	v_lshlrev_b32_e32 v5, 3, v3
	v_lshrrev_b32_e32 v3, 2, v3
	s_add_i32 s0, s28, 0x7ff
	v_and_b32_e32 v5, 24, v5
	v_and_or_b32 v3, v3, 3, v82
	v_mul_u32_u24_e32 v0, 0x90, v0
	s_lshr_b32 s69, s0, 6
	v_lshl_add_u32 v83, v2, 4, v0
	v_and_or_b32 v0, v4, 32, v5
	v_lshlrev_b32_e32 v2, 6, v3
	s_movk_i32 s0, 0x2400
	v_mov_b32_e32 v14, v1
	v_mov_b32_e32 v15, v1
	s_cmp_lt_u32 s69, 1
	s_cbranch_scc1 .Ldsa_p1_done
	s_add_i32 m0, s18, 0x4400
	s_mov_b64 s[100:101], 0xf4000
	global_load_lds_dwordx4 v[90:91], off
	v_lshl_add_u64 v[90:91], v[90:91], 0, s[100:101]
	s_cmp_gt_i32 s29, 0
	s_cbranch_scc1 .Ldsa_p1_b
	s_add_i32 m0, s18, 0x6400
	s_nop 0
	global_load_lds_dwordx4 v[92:93], off
	v_lshl_add_u64 v[92:93], v[92:93], 0, s[100:101]
.Ldsa_p1_b:
	s_add_i32 m0, s18, 0x6800
	s_nop 0
	global_load_lds_dwordx4 v[94:95], off
	v_lshl_add_u64 v[94:95], v[94:95], 0, s[100:101]
.Ldsa_p1_done:
	s_waitcnt vmcnt(0)
	v_or3_b32 v99, v0, v2, s0
	v_mov_b32_e32 v0, v1
	v_mov_b32_e32 v2, v1
	v_mov_b32_e32 v3, v1
	v_mov_b32_e32 v4, v1
	v_mov_b32_e32 v5, v1
	v_mov_b32_e32 v6, v1
	v_mov_b32_e32 v7, v1
	v_mov_b32_e32 v8, v1
	v_mov_b32_e32 v9, v1
	v_mov_b32_e32 v10, v1
	v_mov_b32_e32 v11, v1
	v_mov_b32_e32 v12, v1
	v_mov_b32_e32 v13, v1
	v_mov_b64_e32 v[32:33], v[14:15]
	v_mov_b64_e32 v[30:31], v[12:13]
	v_mov_b64_e32 v[28:29], v[10:11]
	v_mov_b64_e32 v[26:27], v[8:9]
	v_mov_b64_e32 v[24:25], v[6:7]
	v_mov_b64_e32 v[22:23], v[4:5]
	v_mov_b64_e32 v[20:21], v[2:3]
	v_mov_b64_e32 v[18:19], v[0:1]
	v_mov_b64_e32 v[16:17], v[14:15]
	s_add_i32 s73, s18, 0
	s_add_i32 s86, s28, 0x7a1
	s_waitcnt lgkmcnt(0)
	v_mov_b32_e32 v89, v88
	s_add_i32 s87, s69, 1
	v_sub_u32_e32 v118, v247, v82
	s_mov_b32 s0, 0
	v_mov_b32_e32 v119, 0
	v_mov_b32_e32 v98, 0xefa18f08
	s_mov_b32 s94, 64
	v_mov_b64_e32 v[14:15], v[12:13]
	v_mov_b64_e32 v[12:13], v[10:11]
	v_mov_b64_e32 v[10:11], v[8:9]
	v_mov_b64_e32 v[8:9], v[6:7]
	v_mov_b64_e32 v[6:7], v[4:5]
	v_mov_b64_e32 v[4:5], v[2:3]
	v_mov_b64_e32 v[2:3], v[0:1]
	s_mov_b64 s[28:29], 0xf4000
	s_mov_b32 s100, 0
	s_mov_b32 s101, 0x8800
	s_waitcnt vmcnt(0)
	s_barrier
	s_add_i32 s95, s0, 1
	s_cmp_ge_u32 s0, s69
	s_cbranch_scc1 .LBB0_1333
.LBB0_1328:
	s_lshr_b32 s54, s94, 3
	v_lshl_add_u64 v[34:35], v[96:97], 0, s[54:55]
	global_load_dwordx2 v[100:101], v[34:35], off
	s_cmp_ge_u32 s95, s69
	s_cbranch_scc1 .LBB0_1334
	s_mov_b32 s1, s101
	s_andn2_b64 vcc, exec, s[12:13]
	s_cbranch_vccz .LBB0_1346
	s_andn2_b64 vcc, exec, s[14:15]
	s_cbranch_vccz .LBB0_1347

; DI int crow(int reg, int hi) { return (reg & 3) + 8 * (reg >> 2) + 4 * hi; }
; template <int DQK, int W1, int DV, int VW, int MODE> ...
;     ...
; #pragma unroll
;       for (int ii = 0; ii < NVS; ++ii) {
;         const int i = wv + 8 * ii;
;         if (i < NVI) { __builtin_amdgcn_global_load_lds((const unsigned*)vptr[ii], (lds_u32p)(smem + bofs + 64 * KSTR + i * 1024), 16, 0, 0); vptr[ii] += 64 * ldv; }
;       }
;     ...
;     if (!(MODE == 0 && kb > tq0 + 31)) {
;       f32x16 s[2];
;       s[0] = s_block<KSTR, ND, 0>(bufa + klane, qf, negm);
;       s[1] = s_block<KSTR, ND, 1>(bufa + klane, qf, negm);
;       if (MODE == 0) {
;         if (__builtin_amdgcn_readfirstlane((int)(kb + 63 > tq0))) {
; #pragma unroll
;           for (int n = 0; n < 2; ++n)
; #pragma unroll
;             for (int i = 0; i < 16; ++i) { const int key = kb + 32 * n + crow(i, hi); if (key > tq) s[n][i] = NEGV; }
;         }
;       } else if (MODE == 1) {
;         const bool far = (tq0 - (kb + 63)) >= 128;
; #pragma unroll
;         for (int n = 0; n < 2; ++n) {
;           const unsigned wb = (n ? mw1 : mw0) >> (4 * hi);
;           if (far) {
; #pragma unroll
;             for (int i = 0; i < 16; ++i) {
;               const float v = fmaf(s[n][i], c2, bias_far);
;               s[n][i] = ((wb >> ((i & 3) + 8 * (i >> 2))) & 1u) ? v : NEGV;
;             }
;           } else {
; #pragma unroll
;             for (int i = 0; i < 16; ++i) {
;               const int key = kb + 32 * n + crow(i, hi);
;               int rel = tq - key; rel = rel < 0 ? 0 : (rel > 128 ? 128 : rel);
;               const float v = fmaf(s[n][i], c2, lutw[rel]);
;               s[n][i] = ((wb >> ((i & 3) + 8 * (i >> 2))) & 1u) ? v : NEGV;
;             }
;           }
.LBB0_1331:
	s_add_i32 s1, s73, s1
	s_add_i32 m0, s1, 0x2400
	s_nop 0
	global_load_lds_dwordx4 v[94:95], off
	v_lshl_add_u64 v[94:95], v[94:95], 0, s[28:29]
.LBB0_1332:
	s_branch .LBB0_1334
.LBB0_1333:
	v_mov_b64_e32 v[100:101], v[116:117]
.LBB0_1334:
	s_mov_b32 s54, s100
	v_add_u32_e32 v0, s54, v83
	ds_read_b128 v[34:37], v0 offset:0
	ds_read_b128 v[38:41], v0 offset:32
	ds_read_b128 v[42:45], v0 offset:64
	ds_read_b128 v[46:49], v0 offset:0x60
	s_waitcnt lgkmcnt(0)
	v_lshrrev_b32_e32 v121, v82, v116
	v_mfma_f32_32x32x16_bf16 v[50:65], v[34:37], v[66:69], 0
	ds_read_b128 v[34:37], v0 offset:0x1200
	ds_read_b128 v[102:105], v0 offset:0x1220
	ds_read_b128 v[106:109], v0 offset:0x1240
	ds_read_b128 v[110:113], v0 offset:0x1260
	s_waitcnt lgkmcnt(0)
	s_cmpk_lt_i32 s86, 0x80
	v_and_b32_e32 v122, 0x4000000, v121
	s_cselect_b64 s[18:19], -1, 0
	s_cmpk_gt_i32 s86, 0x7f
	s_mov_b64 s[0:1], -1
	v_add_u32_e32 v0, s86, v118
	v_mfma_f32_32x32x16_bf16 v[50:65], v[38:41], v[70:73], v[50:65]
	v_and_b32_e32 v135, 2, v121
	v_and_b32_e32 v136, 1, v121
	v_and_b32_e32 v133, 8, v121
	v_and_b32_e32 v134, 4, v121
	v_and_b32_e32 v130, 0x200, v121
	v_and_b32_e32 v132, 0x100, v121
	v_and_b32_e32 v128, 0x800, v121
	v_mfma_f32_32x32x16_bf16 v[50:65], v[42:45], v[74:77], v[50:65]
	v_and_b32_e32 v131, 0x400, v121
	v_and_b32_e32 v127, 0x20000, v121
	v_and_b32_e32 v129, 0x10000, v121
	v_and_b32_e32 v125, 0x80000, v121
	v_and_b32_e32 v126, 0x40000, v121
	v_and_b32_e32 v123, 0x2000000, v121
	v_and_b32_e32 v124, 0x1000000, v121
	v_mfma_f32_32x32x16_bf16 v[50:65], v[46:49], v[78:81], v[50:65]
	v_cmp_ne_u32_e32 vcc, 0, v122
	v_mfma_f32_32x32x16_bf16 v[34:49], v[34:37], v[66:69], 0
	v_mfma_f32_32x32x16_bf16 v[34:49], v[102:105], v[70:73], v[34:49]
	v_mfma_f32_32x32x16_bf16 v[34:49], v[106:109], v[74:77], v[34:49]
	v_mfma_f32_32x32x16_bf16 v[34:49], v[110:113], v[78:81], v[34:49]
	s_cbranch_scc1 .LBB0_1336
	v_add_u32_e32 v102, 0xfffff85f, v0
	v_add_u32_e32 v103, 0xfffff85e, v0
	v_med3_i32 v102, v102, 0, v233
	v_med3_i32 v103, v103, 0, v233
	v_lshl_add_u32 v102, v102, 2, s27
	v_lshl_add_u32 v103, v103, 2, s27
	v_add_u32_e32 v104, 0xfffff85d, v0
	v_add_u32_e32 v105, 0xfffff85c, v0
	ds_read_b32 v102, v102
	ds_read_b32 v103, v103
	v_med3_i32 v104, v104, 0, v233
	v_med3_i32 v105, v105, 0, v233
	v_lshl_add_u32 v104, v104, 2, s27
	v_lshl_add_u32 v105, v105, 2, s27
	v_add_u32_e32 v106, 0xfffff857, v0
	v_add_u32_e32 v107, 0xfffff856, v0
	ds_read_b32 v104, v104
	ds_read_b32 v105, v105
	v_med3_i32 v106, v106, 0, v233
	v_med3_i32 v107, v107, 0, v233
	v_add_u32_e32 v108, 0xfffff855, v0
	v_add_u32_e32 v109, 0xfffff854, v0
	v_lshl_add_u32 v106, v106, 2, s27
	v_lshl_add_u32 v107, v107, 2, s27
	v_med3_i32 v108, v108, 0, v233
	v_med3_i32 v109, v109, 0, v233
	ds_read_b32 v106, v106
	ds_read_b32 v107, v107
	v_lshl_add_u32 v108, v108, 2, s27
	v_lshl_add_u32 v109, v109, 2, s27
	v_cmp_ne_u32_e64 s[0:1], 0, v136
	ds_read_b32 v108, v108
	ds_read_b32 v109, v109
	s_waitcnt lgkmcnt(0)
	v_pk_fma_f32 v[102:103], v[50:51], s[64:65], v[102:103] op_sel_hi:[1,0,1]
	v_add_u32_e32 v110, 0xfffff84f, v0
	v_add_u32_e32 v111, 0xfffff84e, v0
	v_cndmask_b32_e64 v102, v232, v102, s[0:1]
	v_cmp_ne_u32_e64 s[0:1], 0, v135
	v_med3_i32 v110, v110, 0, v233
	v_med3_i32 v111, v111, 0, v233
	v_cndmask_b32_e64 v103, v232, v103, s[0:1]
	v_pk_fma_f32 v[104:105], v[52:53], s[64:65], v[104:105] op_sel_hi:[1,0,1]
	v_cmp_ne_u32_e64 s[0:1], 0, v134
	v_lshl_add_u32 v110, v110, 2, s27
	v_lshl_add_u32 v111, v111, 2, s27
	v_add_u32_e32 v112, 0xfffff84d, v0
	v_add_u32_e32 v113, 0xfffff84c, v0
	v_cndmask_b32_e64 v104, v232, v104, s[0:1]
	v_cmp_ne_u32_e64 s[0:1], 0, v133
	ds_read_b32 v110, v110
	ds_read_b32 v111, v111
	v_med3_i32 v112, v112, 0, v233
	v_med3_i32 v113, v113, 0, v233
	v_cndmask_b32_e64 v105, v232, v105, s[0:1]
	v_pk_fma_f32 v[106:107], v[54:55], s[64:65], v[106:107] op_sel_hi:[1,0,1]
	v_cmp_ne_u32_e64 s[0:1], 0, v132
	v_lshl_add_u32 v112, v112, 2, s27
	v_lshl_add_u32 v113, v113, 2, s27
	v_add_u32_e32 v114, 0xfffff847, v0
	v_add_u32_e32 v115, 0xfffff846, v0
	v_cndmask_b32_e64 v106, v232, v106, s[0:1]
	v_cmp_ne_u32_e64 s[0:1], 0, v130
	ds_read_b32 v112, v112
	ds_read_b32 v113, v113
	v_med3_i32 v114, v114, 0, v233
	v_med3_i32 v115, v115, 0, v233
	v_add_u32_e32 v116, 0xfffff845, v0
	v_add_u32_e32 v120, 0xfffff844, v0
	v_cndmask_b32_e64 v107, v232, v107, s[0:1]
	v_pk_fma_f32 v[108:109], v[56:57], s[64:65], v[108:109] op_sel_hi:[1,0,1]
	v_cmp_ne_u32_e64 s[0:1], 0, v131
	v_lshl_add_u32 v114, v114, 2, s27
	v_lshl_add_u32 v115, v115, 2, s27
	v_med3_i32 v116, v116, 0, v233
	v_med3_i32 v120, v120, 0, v233
	v_cndmask_b32_e64 v108, v232, v108, s[0:1]
	v_cmp_ne_u32_e64 s[0:1], 0, v128
	ds_read_b32 v114, v114
	ds_read_b32 v115, v115
	v_lshl_add_u32 v116, v116, 2, s27
	v_lshl_add_u32 v120, v120, 2, s27
	v_cndmask_b32_e64 v109, v232, v109, s[0:1]
	v_cmp_ne_u32_e64 s[0:1], 0, v129
	ds_read_b32 v116, v116
	ds_read_b32 v120, v120
	s_waitcnt lgkmcnt(0)
	v_pk_fma_f32 v[110:111], v[58:59], s[64:65], v[110:111] op_sel_hi:[1,0,1]
	v_pk_fma_f32 v[112:113], v[60:61], s[64:65], v[112:113] op_sel_hi:[1,0,1]
	v_cndmask_b32_e64 v110, v232, v110, s[0:1]
	v_cmp_ne_u32_e64 s[0:1], 0, v127
	v_pk_fma_f32 v[114:115], v[62:63], s[64:65], v[114:115] op_sel_hi:[1,0,1]
	v_fmac_f32_e32 v116, 0x3e38aa3b, v64
	v_cndmask_b32_e64 v111, v232, v111, s[0:1]
	v_cmp_ne_u32_e64 s[0:1], 0, v126
	v_cndmask_b32_e32 v116, v232, v116, vcc
	v_fmac_f32_e32 v120, 0x3e38aa3b, v65
	v_cndmask_b32_e64 v112, v232, v112, s[0:1]
	v_cmp_ne_u32_e64 s[0:1], 0, v125
	s_nop 1
	v_cndmask_b32_e64 v113, v232, v113, s[0:1]
	v_cmp_ne_u32_e64 s[0:1], 0, v124
	s_nop 1
	v_cndmask_b32_e64 v114, v232, v114, s[0:1]
	v_cmp_ne_u32_e64 s[0:1], 0, v123
	s_nop 1
	v_cndmask_b32_e64 v115, v232, v115, s[0:1]
	s_mov_b64 s[0:1], 0

; template <int DQK, int W1, int DV, int VW, int MODE> ...
;     ...
;       {
;         f32x16 e0 = s[0], e1 = s[1];
;         if (MODE != 0) { const float nm = -m; e0 = e0 + nm; e1 = e1 + nm; }
; #pragma unroll
;         for (int i = 0; i < 16; ++i) { e0[i] = __builtin_amdgcn_exp2f(e0[i]); e1[i] = __builtin_amdgcn_exp2f(e1[i]); }
;         s[0] = e0; s[1] = e1;
;         const f32x16 sm = e0 + e1;
;         typedef __attribute__((ext_vector_type(8))) float f32x8;
;         const f32x8 h8 = sm.lo + sm.hi;
;         const f32x4 h4 = h8.lo + h8.hi;
;         const f32x2 h2 = h4.lo + h4.hi;
;         l += h2[0] + h2[1];
;       }
;       bf16x8 pb[2][2];
; #pragma unroll
;       for (int n = 0; n < 2; ++n)
; #pragma unroll
;         for (int s2 = 0; s2 < 2; ++s2) {
;           u32x4 pw = {pk2(s[n][8 * s2 + 0], s[n][8 * s2 + 1]), pk2(s[n][8 * s2 + 2], s[n][8 * s2 + 3]),
;                       pk2(s[n][8 * s2 + 4], s[n][8 * s2 + 5]), pk2(s[n][8 * s2 + 6], s[n][8 * s2 + 7])};
;           pb[n][s2] = __builtin_bit_cast(bf16x8, pw);
;         }
;       pv_block<0>(o[0], bufa + vlane, pb);
;       if constexpr (NCB > 1) pv_block<1>(o[1], bufa + vlane, pb);
;       if constexpr (NCB > 2) pv_block<2>(o[2], bufa + vlane, pb);
;       if constexpr (NCB > 3) pv_block<3>(o[3], bufa + vlane, pb);
;     }
;     asm volatile("s_waitcnt vmcnt(0)" ::: "memory");
;     __syncthreads();
.LBB0_1344:
	v_pk_add_f32 v[34:35], v[116:117], v[98:99] op_sel_hi:[1,0] neg_lo:[0,1] neg_hi:[0,1]
	v_pk_add_f32 v[36:37], v[114:115], v[98:99] op_sel_hi:[1,0] neg_lo:[0,1] neg_hi:[0,1]
	v_pk_add_f32 v[38:39], v[112:113], v[98:99] op_sel_hi:[1,0] neg_lo:[0,1] neg_hi:[0,1]
	v_pk_add_f32 v[40:41], v[110:111], v[98:99] op_sel_hi:[1,0] neg_lo:[0,1] neg_hi:[0,1]
	v_pk_add_f32 v[42:43], v[108:109], v[98:99] op_sel_hi:[1,0] neg_lo:[0,1] neg_hi:[0,1]
	v_pk_add_f32 v[44:45], v[106:107], v[98:99] op_sel_hi:[1,0] neg_lo:[0,1] neg_hi:[0,1]
	v_pk_add_f32 v[46:47], v[104:105], v[98:99] op_sel_hi:[1,0] neg_lo:[0,1] neg_hi:[0,1]
	v_pk_add_f32 v[48:49], v[102:103], v[98:99] op_sel_hi:[1,0] neg_lo:[0,1] neg_hi:[0,1]
	v_pk_add_f32 v[64:65], v[64:65], v[98:99] op_sel_hi:[1,0] neg_lo:[0,1] neg_hi:[0,1]
	v_pk_add_f32 v[62:63], v[62:63], v[98:99] op_sel_hi:[1,0] neg_lo:[0,1] neg_hi:[0,1]
	v_pk_add_f32 v[60:61], v[60:61], v[98:99] op_sel_hi:[1,0] neg_lo:[0,1] neg_hi:[0,1]
	v_pk_add_f32 v[58:59], v[58:59], v[98:99] op_sel_hi:[1,0] neg_lo:[0,1] neg_hi:[0,1]
	v_pk_add_f32 v[56:57], v[56:57], v[98:99] op_sel_hi:[1,0] neg_lo:[0,1] neg_hi:[0,1]
	v_pk_add_f32 v[54:55], v[54:55], v[98:99] op_sel_hi:[1,0] neg_lo:[0,1] neg_hi:[0,1]
	v_pk_add_f32 v[52:53], v[52:53], v[98:99] op_sel_hi:[1,0] neg_lo:[0,1] neg_hi:[0,1]
	v_pk_add_f32 v[50:51], v[50:51], v[98:99] op_sel_hi:[1,0] neg_lo:[0,1] neg_hi:[0,1]
	v_exp_f32_e32 v48, v48
	v_exp_f32_e32 v50, v50
	v_exp_f32_e32 v49, v49
	v_exp_f32_e32 v51, v51
	v_exp_f32_e32 v46, v46
	v_exp_f32_e32 v52, v52
	v_exp_f32_e32 v47, v47
	v_exp_f32_e32 v53, v53
	v_exp_f32_e32 v44, v44
	v_exp_f32_e32 v54, v54
	v_exp_f32_e32 v45, v45
	v_exp_f32_e32 v55, v55
	v_exp_f32_e32 v42, v42
	v_exp_f32_e32 v56, v56
	v_exp_f32_e32 v43, v43
	v_exp_f32_e32 v57, v57
	v_exp_f32_e32 v102, v40
	v_exp_f32_e32 v58, v58
	v_exp_f32_e32 v103, v41
	v_exp_f32_e32 v59, v59
	v_exp_f32_e32 v104, v38
	v_exp_f32_e32 v60, v60
	v_exp_f32_e32 v105, v39
	v_exp_f32_e32 v61, v61
	v_exp_f32_e32 v36, v36
	v_exp_f32_e32 v62, v62
	v_exp_f32_e32 v37, v37
	v_exp_f32_e32 v63, v63
	v_exp_f32_e32 v34, v34
	v_exp_f32_e32 v64, v64
	v_exp_f32_e32 v35, v35
	v_exp_f32_e32 v65, v65
	v_pk_add_f32 v[38:39], v[102:103], v[58:59]
	v_pk_add_f32 v[40:41], v[104:105], v[60:61]
	v_pk_add_f32 v[106:107], v[46:47], v[52:53]
	v_pk_add_f32 v[108:109], v[34:35], v[64:65]
	v_pk_add_f32 v[110:111], v[42:43], v[56:57]
	v_pk_add_f32 v[112:113], v[36:37], v[62:63]
	v_pk_add_f32 v[114:115], v[44:45], v[54:55]
	v_pk_add_f32 v[116:117], v[48:49], v[50:51]
	v_pk_add_f32 v[112:113], v[114:115], v[112:113]
	v_pk_add_f32 v[108:109], v[110:111], v[108:109]
	v_pk_add_f32 v[40:41], v[106:107], v[40:41]
	v_pk_add_f32 v[38:39], v[116:117], v[38:39]
	v_pk_add_f32 v[40:41], v[40:41], v[108:109]
	v_pk_add_f32 v[38:39], v[38:39], v[112:113]
	s_sub_i32 s86, s86, 64
	v_pk_add_f32 v[38:39], v[38:39], v[40:41]
	v_cvt_pk_bf16_f32 v40, v44, v45
	v_add_f32_e32 v0, v38, v39
	v_cvt_pk_bf16_f32 v38, v48, v49
	v_cvt_pk_bf16_f32 v39, v46, v47
	v_cvt_pk_bf16_f32 v41, v42, v43
	v_cvt_pk_bf16_f32 v44, v36, v37
	v_cvt_pk_bf16_f32 v45, v34, v35
	v_cvt_pk_bf16_f32 v46, v50, v51
	v_cvt_pk_bf16_f32 v47, v52, v53
	v_cvt_pk_bf16_f32 v48, v54, v55
	v_cvt_pk_bf16_f32 v49, v56, v57
	v_cvt_pk_bf16_f32 v34, v58, v59
	v_cvt_pk_bf16_f32 v35, v60, v61
	v_cvt_pk_bf16_f32 v36, v62, v63
	v_cvt_pk_bf16_f32 v37, v64, v65
	v_add_f32_e32 v119, v119, v0
	v_add_u32_e32 v0, s54, v99
	ds_read_b64_tr_b16 v[62:63], v0 offset:0
	ds_read_b64_tr_b16 v[64:65], v0 offset:0x200
	ds_read_b64_tr_b16 v[58:59], v0 offset:0x400
	ds_read_b64_tr_b16 v[60:61], v0 offset:0x600
	ds_read_b64_tr_b16 v[54:55], v0 offset:0x800
	ds_read_b64_tr_b16 v[56:57], v0 offset:0xa00
	ds_read_b64_tr_b16 v[50:51], v0 offset:0xc00
	ds_read_b64_tr_b16 v[52:53], v0 offset:0xe00
	s_waitcnt lgkmcnt(0)
	v_cvt_pk_bf16_f32 v42, v102, v103
	v_mfma_f32_32x32x16_bf16 v[18:33], v[62:65], v[38:41], v[18:33]
	v_cvt_pk_bf16_f32 v43, v104, v105
	s_add_i32 s94, s94, 64
	s_cmp_lg_u32 s87, s95
	v_mfma_f32_32x32x16_bf16 v[18:33], v[58:61], v[42:45], v[18:33]
	v_mfma_f32_32x32x16_bf16 v[18:33], v[54:57], v[46:49], v[18:33]
	v_mfma_f32_32x32x16_bf16 v[18:33], v[50:53], v[34:37], v[18:33]
	ds_read_b64_tr_b16 v[62:63], v0 offset:0x1000
	ds_read_b64_tr_b16 v[64:65], v0 offset:0x1200
	ds_read_b64_tr_b16 v[58:59], v0 offset:0x1400
	ds_read_b64_tr_b16 v[60:61], v0 offset:0x1600
	ds_read_b64_tr_b16 v[54:55], v0 offset:0x1800
	ds_read_b64_tr_b16 v[56:57], v0 offset:0x1a00
	ds_read_b64_tr_b16 v[50:51], v0 offset:0x1c00
	ds_read_b64_tr_b16 v[52:53], v0 offset:0x1e00
	s_waitcnt lgkmcnt(0)
	s_cmp_ge_u32 s95, s69
	s_cbranch_scc1 .Ldsa_w0
	s_waitcnt vmcnt(2)
	s_branch .Ldsa_wd

; template <int DQK, int W1, int DV, int VW, int MODE> ...
;     ...
;       pv_block<0>(o[0], bufa + vlane, pb);
;       if constexpr (NCB > 1) pv_block<1>(o[1], bufa + vlane, pb);
;       if constexpr (NCB > 2) pv_block<2>(o[2], bufa + vlane, pb);
;       if constexpr (NCB > 3) pv_block<3>(o[3], bufa + vlane, pb);
;     }
;     asm volatile("s_waitcnt vmcnt(0)" ::: "memory");
;     __syncthreads();
.Ldsa_wd:
	s_mov_b32 s101, s100
	s_add_u32 s100, s100, 0x4400
	s_cmp_eq_u32 s100, 0xcc00
	s_cselect_b32 s100, 0, s100
	s_waitcnt lgkmcnt(0)
	s_barrier
	v_mfma_f32_32x32x16_bf16 v[2:17], v[62:65], v[38:41], v[2:17]
	v_mfma_f32_32x32x16_bf16 v[2:17], v[58:61], v[42:45], v[2:17]
	v_mfma_f32_32x32x16_bf16 v[2:17], v[54:57], v[46:49], v[2:17]
	v_mfma_f32_32x32x16_bf16 v[2:17], v[50:53], v[34:37], v[2:17]
	s_cmp_lg_u32 s87, s95
	s_cbranch_scc0 .LBB0_1348
	s_mov_b32 s0, s95
	v_mov_b64_e32 v[116:117], v[100:101]
	s_add_i32 s95, s0, 1
	s_cmp_ge_u32 s0, s69
	s_cbranch_scc1 .LBB0_1333
	s_branch .LBB0_1328

; template <int DQK, int W1, int DV, int VW, int MODE> ...
;     ...
;   auto stage_tile = [&](int kb, int buf) {
;     const unsigned bofs = (unsigned)(buf * BUF);
;     if (MODE != 2) {
; #pragma unroll
;       for (int ii = 0; ii < NKS; ++ii) {
;         const int i = wv + 8 * ii;
;         if (i < NKI) { __builtin_amdgcn_global_load_lds((const unsigned*)kptr[ii], (lds_u32p)(smem + bofs + i * 1024), 16, 0, 0); kptr[ii] += kstr[ii]; }
;       }
; #pragma unroll
;       for (int ii = 0; ii < NVS; ++ii) {
;         const int i = wv + 8 * ii;
;         if (i < NVI) { __builtin_amdgcn_global_load_lds((const unsigned*)vptr[ii], (lds_u32p)(smem + bofs + 64 * KSTR + i * 1024), 16, 0, 0); vptr[ii] += 64 * ldv; }
;       }
;     ...
;   stage_tile(kbase0, 0);
;   asm volatile("s_waitcnt vmcnt(0)" ::: "memory");
;   __syncthreads();
.LBB0_1379:
	s_add_i32 m0, s30, 0xa400
	v_lshlrev_b32_e32 v206, 1, v2
	global_load_lds_dwordx4 v[190:191], off
	v_lshl_add_u64 v[190:191], v[190:191], 0, v[0:1]
	s_add_i32 m0, s30, 0xc400
	v_mov_b32_e32 v195, v1
	global_load_lds_dwordx4 v[192:193], off
	v_lshl_add_u64 v[192:193], v[192:193], 0, v[194:195]
	s_add_i32 m0, s30, 0xe400
	v_mov_b32_e32 v199, v1
	global_load_lds_dwordx4 v[196:197], off
	v_lshl_add_u64 v[196:197], v[196:197], 0, v[198:199]
	s_cmp_gt_i32 s31, 0
	s_cbranch_scc1 .Lmla_p1_skip
	s_add_i32 m0, s30, 0x10400
	v_mov_b32_e32 v207, v1
	global_load_lds_dwordx4 v[200:201], off
	v_lshl_add_u64 v[200:201], v[200:201], 0, v[206:207]
.Lmla_p1_skip:
	s_add_i32 m0, s30, 0x10800
	s_mov_b64 s[8:9], 0x80000
	global_load_lds_dwordx4 v[202:203], off
	v_lshl_add_u64 v[202:203], v[202:203], 0, s[8:9]
	s_add_i32 m0, s30, 0x12800
	s_nop 0
	global_load_lds_dwordx4 v[204:205], off
	v_lshl_add_u64 v[204:205], v[204:205], 0, s[8:9]
	s_waitcnt vmcnt(0)
	v_lshlrev_b32_e32 v188, 2, v26
	s_cmpk_gt_i32 s26, 0x3ff
	s_waitcnt vmcnt(0) lgkmcnt(0)
	s_barrier
	s_cbranch_scc1 .LBB0_1415
	v_cndmask_b32_e64 v3, 0, 1, s[10:11]
	v_cmp_ne_u32_e64 s[8:9], 1, v3
	s_andn2_b64 vcc, exec, s[10:11]
	s_add_i32 s26, s30, 0
	s_cbranch_vccz .LBB0_1416
	v_cndmask_b32_e64 v3, 0, 1, s[12:13]
	v_cmp_ne_u32_e64 s[10:11], 1, v3
	s_andn2_b64 vcc, exec, s[12:13]
	s_cbranch_vccz .LBB0_1417

; template <int DQK, int W1, int DV, int VW, int MODE> ...
;     ...
;   auto stage_tile = [&](int kb, int buf) {
;     const unsigned bofs = (unsigned)(buf * BUF);
;     if (MODE != 2) {
; #pragma unroll
;       for (int ii = 0; ii < NKS; ++ii) {
;         const int i = wv + 8 * ii;
;         if (i < NKI) { __builtin_amdgcn_global_load_lds((const unsigned*)kptr[ii], (lds_u32p)(smem + bofs + i * 1024), 16, 0, 0); kptr[ii] += kstr[ii]; }
.LBB0_1383:
	s_add_i32 m0, s26, 0x18800
	v_mov_b32_e32 v199, v1
	global_load_lds_dwordx4 v[196:197], off
	v_lshl_add_u64 v[196:197], v[196:197], 0, v[198:199]

; template <int DQK, int W1, int DV, int VW, int MODE> ...
;     ...
; #pragma unroll
;       for (int ii = 0; ii < NVS; ++ii) {
;         const int i = wv + 8 * ii;
;         if (i < NVI) { __builtin_amdgcn_global_load_lds((const unsigned*)vptr[ii], (lds_u32p)(smem + bofs + 64 * KSTR + i * 1024), 16, 0, 0); vptr[ii] += 64 * ldv; }
;       }
.LBB0_1387:
	s_add_i32 m0, s26, 0x1cc00
	s_mov_b64 s[0:1], 0x80000
	global_load_lds_dwordx4 v[204:205], off
	v_lshl_add_u64 v[204:205], v[204:205], 0, s[0:1]

; template <int DQK, int W1, int DV, int VW, int MODE> ...
;     ...
;   stage_tile(kbase0, 0);
;   asm volatile("s_waitcnt vmcnt(0)" ::: "memory");
;   __syncthreads();
;   for (int t = 0; t < ntiles; ++t) {
.LBB0_1394:
	s_waitcnt vmcnt(6)
	s_sub_i32 s29, 0, s29
	s_lshl_b32 s1, s28, 2
	s_or_b32 s0, s54, 31
	s_add_i32 s1, s1, 4
	s_lshl_b32 s28, s29, 2
	s_movk_i32 s29, 0xffe1
	s_movk_i32 s69, 0x7f
	s_mov_b32 s100, 0xa400
	s_mov_b32 s101, 0
	s_waitcnt lgkmcnt(0)
	s_barrier
	s_branch .LBB0_1397

; template <int DQK, int W1, int DV, int VW, int MODE> ...
;     ...
;     asm volatile("s_waitcnt vmcnt(0)" ::: "memory");
;     __syncthreads();
.LBB0_1396:
	s_add_i32 s30, s29, 34
	s_cmp_ge_i32 s30, s1
	s_cbranch_scc1 .Lmla_w0
	s_waitcnt vmcnt(5)
	s_branch .Lmla_wd

; template <int DQK, int W1, int DV, int VW, int MODE> ...
;     ...
;   for (int t = 0; t < ntiles; ++t) {
;     const int kb = kbase0 + t * 64;
;     const unsigned bufa = lds0 + (unsigned)((t & 1) * BUF);
;     const unsigned mw0 = mwn[0], mw1 = mwn[1];
;     if (t + 1 < ntiles) stage_tile(kb + 64, (t + 1) & 1);
;     ...
;     asm volatile("s_waitcnt vmcnt(0)" ::: "memory");
;     __syncthreads();
.Lmla_wd:
	s_mov_b32 s101, s100
	s_add_u32 s100, s100, 0xa400
	s_cmp_eq_u32 s100, 0x1ec00
	s_cselect_b32 s100, 0, s100
	s_add_i32 s29, s29, 1
	s_add_i32 s69, s69, 64
	s_cmp_eq_u32 s28, s29
	s_waitcnt lgkmcnt(0)
	s_barrier
	s_cbranch_scc1 .LBB0_1238
.LBB0_1397:
	s_add_i32 s30, s29, 34
	s_cmp_ge_i32 s30, s1
	s_cbranch_scc1 .LBB0_1405
	s_mov_b32 s30, s101
	s_and_b64 vcc, exec, s[8:9]
	s_cbranch_vccz .LBB0_1410
	s_and_b64 vcc, exec, s[10:11]
	s_cbranch_vccz .LBB0_1411

; DI int crow(int reg, int hi) { return (reg & 3) + 8 * (reg >> 2) + 4 * hi; }
; template <int DQK, int W1, int DV, int VW, int MODE> ...
;     ...
;     if (!(MODE == 0 && kb > tq0 + 31)) {
;       f32x16 s[2];
;       s[0] = s_block<KSTR, ND, 0>(bufa + klane, qf, negm);
;       s[1] = s_block<KSTR, ND, 1>(bufa + klane, qf, negm);
;       if (MODE == 0) {
;         if (__builtin_amdgcn_readfirstlane((int)(kb + 63 > tq0))) {
; #pragma unroll
;           for (int n = 0; n < 2; ++n)
; #pragma unroll
;             for (int i = 0; i < 16; ++i) { const int key = kb + 32 * n + crow(i, hi); if (key > tq) s[n][i] = NEGV; }
;         }
.LBB0_1405:
	s_sub_i32 s30, s69, 63
	s_cmp_gt_i32 s30, s0
	s_cbranch_scc1 .LBB0_1396
	s_mov_b32 s31, 0
	s_mov_b32 s70, s100
	v_add_u32_e32 v14, s70, v189
	ds_read_b128 v[2:5], v14 offset:0
	ds_read_b128 v[6:9], v14 offset:32
	ds_read_b128 v[10:13], v14 offset:64
	ds_read_b128 v[112:115], v14 offset:0x60
	s_waitcnt lgkmcnt(0)
	s_cmp_gt_i32 s69, s54
	v_mfma_f32_32x32x16_bf16 v[96:111], v[2:5], v[128:131], v[80:95]
	s_cselect_b64 s[30:31], -1, 0
	v_mfma_f32_32x32x16_bf16 v[96:111], v[6:9], v[132:135], v[96:111]
	v_mfma_f32_32x32x16_bf16 v[96:111], v[10:13], v[136:139], v[96:111]
	v_mfma_f32_32x32x16_bf16 v[96:111], v[112:115], v[140:143], v[96:111]
	ds_read_b128 v[2:5], v14 offset:0x80
	ds_read_b128 v[6:9], v14 offset:0xa0
	ds_read_b128 v[10:13], v14 offset:0xc0
	ds_read_b128 v[112:115], v14 offset:0xe0
	s_waitcnt lgkmcnt(0)
	s_nop 0
	v_mfma_f32_32x32x16_bf16 v[96:111], v[2:5], v[144:147], v[96:111]
	v_mfma_f32_32x32x16_bf16 v[96:111], v[6:9], v[148:151], v[96:111]
	v_mfma_f32_32x32x16_bf16 v[96:111], v[10:13], v[152:155], v[96:111]
	v_mfma_f32_32x32x16_bf16 v[96:111], v[112:115], v[156:159], v[96:111]
	ds_read_b128 v[2:5], v14 offset:0x100
	ds_read_b128 v[6:9], v14 offset:0x120
	ds_read_b128 v[10:13], v14 offset:0x140
	ds_read_b128 v[112:115], v14 offset:0x160
	s_waitcnt lgkmcnt(0)
	s_nop 0
	v_mfma_f32_32x32x16_bf16 v[96:111], v[2:5], v[160:163], v[96:111]
	v_mfma_f32_32x32x16_bf16 v[96:111], v[6:9], v[164:167], v[96:111]
	v_mfma_f32_32x32x16_bf16 v[96:111], v[10:13], v[168:171], v[96:111]
	ds_read_b128 v[2:5], v14 offset:0x3200
	ds_read_b128 v[6:9], v14 offset:0x3220
	ds_read_b128 v[10:13], v14 offset:0x3240
	ds_read_b128 v[208:211], v14 offset:0x3260
	s_waitcnt lgkmcnt(0)
	v_mfma_f32_32x32x16_bf16 v[96:111], v[112:115], v[172:175], v[96:111]
	v_mfma_f32_32x32x16_bf16 v[112:127], v[2:5], v[128:131], v[80:95]
	v_mfma_f32_32x32x16_bf16 v[112:127], v[6:9], v[132:135], v[112:127]
	v_mfma_f32_32x32x16_bf16 v[112:127], v[10:13], v[136:139], v[112:127]
	v_mfma_f32_32x32x16_bf16 v[112:127], v[208:211], v[140:143], v[112:127]
	ds_read_b128 v[2:5], v14 offset:0x3280
	ds_read_b128 v[6:9], v14 offset:0x32a0
	ds_read_b128 v[10:13], v14 offset:0x32c0
	ds_read_b128 v[208:211], v14 offset:0x32e0
	s_waitcnt lgkmcnt(0)
	s_nop 0
	v_mfma_f32_32x32x16_bf16 v[112:127], v[2:5], v[144:147], v[112:127]
	v_mfma_f32_32x32x16_bf16 v[112:127], v[6:9], v[148:151], v[112:127]
	v_mfma_f32_32x32x16_bf16 v[112:127], v[10:13], v[152:155], v[112:127]
	v_mfma_f32_32x32x16_bf16 v[112:127], v[208:211], v[156:159], v[112:127]
	ds_read_b128 v[2:5], v14 offset:0x3300
	ds_read_b128 v[6:9], v14 offset:0x3320
	ds_read_b128 v[10:13], v14 offset:0x3340
	ds_read_b128 v[208:211], v14 offset:0x3360
	s_waitcnt lgkmcnt(0)
	s_nop 0
	v_mfma_f32_32x32x16_bf16 v[112:127], v[2:5], v[160:163], v[112:127]
	v_cndmask_b32_e64 v2, 0, 1, s[30:31]
	s_nop 0
	v_readfirstlane_b32 s30, v2
	s_bitcmp0_b32 s30, 0
	v_mfma_f32_32x32x16_bf16 v[112:127], v[6:9], v[164:167], v[112:127]
	v_mfma_f32_32x32x16_bf16 v[112:127], v[10:13], v[168:171], v[112:127]
	v_mfma_f32_32x32x16_bf16 v[112:127], v[208:211], v[172:175], v[112:127]
	s_cbranch_scc1 .LBB0_1408
	v_add_u32_e32 v2, s69, v188
	v_subrev_u32_e32 v3, 63, v2
	v_cmp_gt_i32_e32 vcc, v3, v186
	s_nop 1
	v_cndmask_b32_e32 v4, v96, v232, vcc
	v_cmp_lt_i32_e32 vcc, v3, v186
	v_subrev_u32_e32 v3, 61, v2
	s_nop 0
	v_cndmask_b32_e32 v96, v4, v96, vcc
	v_cndmask_b32_e32 v97, v232, v97, vcc
	v_cmp_le_i32_e32 vcc, v3, v186
	v_subrev_u32_e32 v3, 60, v2
	s_nop 0
	v_cndmask_b32_e32 v98, v232, v98, vcc
	v_cmp_le_i32_e32 vcc, v3, v186
	v_subrev_u32_e32 v3, 55, v2
	s_nop 0
	v_cndmask_b32_e32 v99, v232, v99, vcc
	v_cmp_le_i32_e32 vcc, v3, v186
	v_subrev_u32_e32 v3, 54, v2
	s_nop 0
	v_cndmask_b32_e32 v100, v232, v100, vcc
	v_cmp_le_i32_e32 vcc, v3, v186
	v_subrev_u32_e32 v3, 53, v2
	s_nop 0
	v_cndmask_b32_e32 v101, v232, v101, vcc
	v_cmp_le_i32_e32 vcc, v3, v186
	v_subrev_u32_e32 v3, 52, v2
	s_nop 0
	v_cndmask_b32_e32 v102, v232, v102, vcc
	v_cmp_le_i32_e32 vcc, v3, v186
	v_subrev_u32_e32 v3, 47, v2
	s_nop 0
	v_cndmask_b32_e32 v103, v232, v103, vcc
	v_cmp_le_i32_e32 vcc, v3, v186
	v_subrev_u32_e32 v3, 46, v2
	s_nop 0
	v_cndmask_b32_e32 v104, v232, v104, vcc
	v_cmp_le_i32_e32 vcc, v3, v186
	v_subrev_u32_e32 v3, 45, v2
	s_nop 0
	v_cndmask_b32_e32 v105, v232, v105, vcc
	v_cmp_le_i32_e32 vcc, v3, v186
	v_subrev_u32_e32 v3, 44, v2
	s_nop 0
	v_cndmask_b32_e32 v106, v232, v106, vcc
	v_cmp_le_i32_e32 vcc, v3, v186
	v_subrev_u32_e32 v3, 39, v2
	s_nop 0
	v_cndmask_b32_e32 v107, v232, v107, vcc
	v_cmp_le_i32_e32 vcc, v3, v186
	v_subrev_u32_e32 v3, 38, v2
	s_nop 0
	v_cndmask_b32_e32 v108, v232, v108, vcc
	v_cmp_le_i32_e32 vcc, v3, v186
	v_subrev_u32_e32 v3, 37, v2
	s_nop 0
	v_cndmask_b32_e32 v109, v232, v109, vcc
	v_cmp_le_i32_e32 vcc, v3, v186
	v_subrev_u32_e32 v3, 36, v2
	s_nop 0
	v_cndmask_b32_e32 v110, v232, v110, vcc
	v_cmp_le_i32_e32 vcc, v3, v186
	v_subrev_u32_e32 v3, 31, v2
	s_nop 0
	v_cndmask_b32_e32 v111, v232, v111, vcc
	v_cmp_le_i32_e32 vcc, v3, v186
	v_subrev_u32_e32 v3, 30, v2
	s_nop 0
	v_cndmask_b32_e32 v112, v232, v112, vcc
	v_cmp_le_i32_e32 vcc, v3, v186
	v_subrev_u32_e32 v3, 29, v2
	s_nop 0
	v_cndmask_b32_e32 v113, v232, v113, vcc
	v_cmp_le_i32_e32 vcc, v3, v186
	v_subrev_u32_e32 v3, 28, v2
	s_nop 0
	v_cndmask_b32_e32 v114, v232, v114, vcc
	v_cmp_le_i32_e32 vcc, v3, v186
	v_subrev_u32_e32 v3, 23, v2
	s_nop 0
	v_cndmask_b32_e32 v115, v232, v115, vcc
	v_cmp_le_i32_e32 vcc, v3, v186
	v_subrev_u32_e32 v3, 22, v2
	s_nop 0
	v_cndmask_b32_e32 v116, v232, v116, vcc
	v_cmp_le_i32_e32 vcc, v3, v186
	v_subrev_u32_e32 v3, 21, v2
	s_nop 0
	v_cndmask_b32_e32 v117, v232, v117, vcc
	v_cmp_le_i32_e32 vcc, v3, v186
	v_subrev_u32_e32 v3, 20, v2
	s_nop 0
	v_cndmask_b32_e32 v118, v232, v118, vcc
	v_cmp_le_i32_e32 vcc, v3, v186
	v_add_u32_e32 v3, -15, v2
	s_nop 0
	v_cndmask_b32_e32 v119, v232, v119, vcc
	v_cmp_le_i32_e32 vcc, v3, v186
	v_add_u32_e32 v3, -14, v2
	s_nop 0
	v_cndmask_b32_e32 v120, v232, v120, vcc
	v_cmp_le_i32_e32 vcc, v3, v186
	v_add_u32_e32 v3, -13, v2
	s_nop 0
	v_cndmask_b32_e32 v121, v232, v121, vcc
	v_cmp_le_i32_e32 vcc, v3, v186
	v_add_u32_e32 v3, -12, v2
	s_nop 0
	v_cndmask_b32_e32 v122, v232, v122, vcc
	v_cmp_le_i32_e32 vcc, v3, v186
	v_add_u32_e32 v3, -7, v2
	s_nop 0
	v_cndmask_b32_e32 v123, v232, v123, vcc
	v_cmp_le_i32_e32 vcc, v3, v186
	v_add_u32_e32 v3, -6, v2
	s_nop 0
	v_cndmask_b32_e32 v124, v232, v124, vcc
	v_cmp_le_i32_e32 vcc, v3, v186
	v_add_u32_e32 v3, -5, v2
	v_add_u32_e32 v2, -4, v2
	v_cndmask_b32_e32 v125, v232, v125, vcc
	v_cmp_le_i32_e32 vcc, v3, v186
	s_nop 1
	v_cndmask_b32_e32 v126, v232, v126, vcc
	v_cmp_le_i32_e32 vcc, v2, v186
	s_nop 1
	v_cndmask_b32_e32 v127, v232, v127, vcc

; template <int DQK, int W1, int DV, int VW, int MODE> ...
;     ...
;   auto stage_tile = [&](int kb, int buf) {
;     const unsigned bofs = (unsigned)(buf * BUF);
;     if (MODE != 2) {
; #pragma unroll
;       for (int ii = 0; ii < NKS; ++ii) {
;         const int i = wv + 8 * ii;
;         if (i < NKI) { __builtin_amdgcn_global_load_lds((const unsigned*)kptr[ii], (lds_u32p)(smem + bofs + i * 1024), 16, 0, 0); kptr[ii] += kstr[ii]; }
;       }
; #pragma unroll
;       for (int ii = 0; ii < NVS; ++ii) {
;         const int i = wv + 8 * ii;
;         if (i < NVI) { __builtin_amdgcn_global_load_lds((const unsigned*)vptr[ii], (lds_u32p)(smem + bofs + 64 * KSTR + i * 1024), 16, 0, 0); vptr[ii] += 64 * ldv; }
;       }
.LBB0_1416:
	s_add_i32 m0, s26, 0x14800
	s_nop 0
	global_load_lds_dwordx4 v[190:191], off
	v_lshl_add_u64 v[190:191], v[190:191], 0, v[0:1]
	v_cndmask_b32_e64 v3, 0, 1, s[12:13]
	v_cmp_ne_u32_e64 s[10:11], 1, v3
	s_andn2_b64 vcc, exec, s[12:13]
	s_cbranch_vccnz .LBB0_1382
.LBB0_1417:
	s_add_i32 m0, s26, 0x16800
	v_mov_b32_e32 v195, v1
	global_load_lds_dwordx4 v[192:193], off
	v_lshl_add_u64 v[192:193], v[192:193], 0, v[194:195]
	v_cndmask_b32_e64 v3, 0, 1, s[14:15]
	v_cmp_ne_u32_e64 s[12:13], 1, v3
	s_andn2_b64 vcc, exec, s[14:15]
	s_cbranch_vccz .LBB0_1383
	s_branch .LBB0_1384
.LBB0_1418:
	s_add_i32 m0, s26, 0x1a800
	v_mov_b32_e32 v207, v1
	global_load_lds_dwordx4 v[200:201], off
	v_lshl_add_u64 v[200:201], v[200:201], 0, v[206:207]
	v_cndmask_b32_e64 v2, 0, 1, s[18:19]
	v_cmp_ne_u32_e64 s[16:17], 1, v2
	s_andn2_b64 vcc, exec, s[18:19]
	s_cbranch_vccnz .LBB0_1386
.LBB0_1419:
	s_add_i32 m0, s26, 0x1ac00
	s_mov_b64 s[18:19], 0x80000
	global_load_lds_dwordx4 v[202:203], off
	v_lshl_add_u64 v[202:203], v[202:203], 0, s[18:19]
	v_cndmask_b32_e64 v2, 0, 1, s[0:1]
	v_cmp_ne_u32_e64 s[18:19], 1, v2
	s_andn2_b64 vcc, exec, s[0:1]
	s_cbranch_vccz .LBB0_1387
	s_branch .LBB0_1388

; __global__ void __launch_bounds__(512, 2) mega(Params p) {
	.amdhsa_kernel _Z4mega6Params
		.amdhsa_group_segment_fixed_size 0
		.amdhsa_private_segment_fixed_size 0
		.amdhsa_kernarg_size 400
		.amdhsa_user_sgpr_count 2
		.amdhsa_user_sgpr_dispatch_ptr 0
		.amdhsa_user_sgpr_queue_ptr 0
		.amdhsa_user_sgpr_kernarg_segment_ptr 1
		.amdhsa_user_sgpr_dispatch_id 0
		.amdhsa_user_sgpr_kernarg_preload_length 0
		.amdhsa_user_sgpr_kernarg_preload_offset 0
		.amdhsa_user_sgpr_private_segment_size 0
		.amdhsa_uses_dynamic_stack 0
		.amdhsa_enable_private_segment 0
		.amdhsa_system_sgpr_workgroup_id_x 1
		.amdhsa_system_sgpr_workgroup_id_y 0
		.amdhsa_system_sgpr_workgroup_id_z 0
		.amdhsa_system_sgpr_workgroup_info 0
		.amdhsa_system_vgpr_workitem_id 2
		.amdhsa_next_free_vgpr 256
		.amdhsa_next_free_sgpr 102
		.amdhsa_accum_offset 256
		.amdhsa_reserve_vcc 1
		.amdhsa_float_round_mode_32 0
		.amdhsa_float_round_mode_16_64 0
		.amdhsa_float_denorm_mode_32 3
		.amdhsa_float_denorm_mode_16_64 3
		.amdhsa_dx10_clamp 1
		.amdhsa_ieee_mode 1
		.amdhsa_fp16_overflow 0
		.amdhsa_tg_split 0
		.amdhsa_exception_fp_ieee_invalid_op 0
		.amdhsa_exception_fp_denorm_src 0
		.amdhsa_exception_fp_ieee_div_zero 0
		.amdhsa_exception_fp_ieee_overflow 0
		.amdhsa_exception_fp_ieee_underflow 0
		.amdhsa_exception_fp_ieee_inexact 0
		.amdhsa_exception_int_div_zero 0
	.end_amdhsa_kernel

; __global__ void __launch_bounds__(512, 2) mega(Params p) {
amdhsa.kernels:
  - .agpr_count:     0
    .args:
      - .offset:         0
        .size:           144
        .value_kind:     by_value
      - .offset:         144
        .size:           4
        .value_kind:     hidden_block_count_x
      - .offset:         148
        .size:           4
        .value_kind:     hidden_block_count_y
      - .offset:         152
        .size:           4
        .value_kind:     hidden_block_count_z
      - .offset:         156
        .size:           2
        .value_kind:     hidden_group_size_x
      - .offset:         158
        .size:           2
        .value_kind:     hidden_group_size_y
      - .offset:         160
        .size:           2
        .value_kind:     hidden_group_size_z
      - .offset:         162
        .size:           2
        .value_kind:     hidden_remainder_x
      - .offset:         164
        .size:           2
        .value_kind:     hidden_remainder_y
      - .offset:         166
        .size:           2
        .value_kind:     hidden_remainder_z
      - .offset:         184
        .size:           8
        .value_kind:     hidden_global_offset_x
      - .offset:         192
        .size:           8
        .value_kind:     hidden_global_offset_y
      - .offset:         200
        .size:           8
        .value_kind:     hidden_global_offset_z
      - .offset:         208
        .size:           2
        .value_kind:     hidden_grid_dims
      - .offset:         232
        .size:           8
        .value_kind:     hidden_multigrid_sync_arg
      - .offset:         264
        .size:           4
        .value_kind:     hidden_dynamic_lds_size
    .group_segment_fixed_size: 0
    .kernarg_segment_align: 8
    .kernarg_segment_size: 400
    .language:       OpenCL C
    .language_version:
      - 2
      - 0
    .max_flat_workgroup_size: 512
    .name:           _Z4mega6Params
    .private_segment_fixed_size: 0
    .sgpr_count:     108
    .sgpr_spill_count: 382
    .symbol:         _Z4mega6Params.kd
    .uniform_work_group_size: 1
    .uses_dynamic_stack: false
    .vgpr_count:     256
    .vgpr_spill_count: 0
    .wavefront_size: 64
